# h7 + DA V tile stored with 144B rows and permuted 8B pieces so V fragments are single ds_read_b128
# speedup vs baseline: 1.0052x; 1.0024x over previous
; #define LAS __attribute__((address_space(3)))
; #define GAS __attribute__((address_space(1)))
; template <int MODE> ...
;     ...
;     if (load_bias) {
;         if (MODE == 0) {
;             float tb[8];
; #pragma unroll
;             for (int k = 0; k < 8; ++k) { const int i = tid + NT_ * k; tb[k] = *(const GAS float*)(biasT + (size_t)(2 * hp + (i >> 11)) * 2048 + (i & 2047)); }
; #pragma unroll
;             for (int k = 0; k < 8; ++k) { const int i = tid + NT_ * k; biasL[i] = tb[k]; }
;         } else {
;             for (int i = tid; i < 2 * 129; i += NT_) { const int mm = i / 129, ii = i - mm * 129; biasL[mm * 2048 + ii] = biasT[(size_t)(2 * hp + mm) * 2048 + min(ii * dil, 2047)]; }
;         }
;     }
;     const int q_lo = 128 * jblk + 32 * wq;
;     const int qi = q_lo + r32;
;     const size_t qtok = tok0 + (size_t)qi * dil;
;     bf16x8 qf[4];
; #pragma unroll
;     for (int ds = 0; ds < 4; ++ds) qf[ds] = *(const GAS bf16x8*)(QK + qtok * 2048 + (2 * hp + mp) * 64 + 16 * ds + 8 * hi);
;     const int kt_hi = 2 * jblk + 1;
;     const int kt_lo = (MODE == 0) ? 0 : ((jblk > 0) ? 2 * jblk - 2 : 0);
;     const int kp_row0 = tid >> 4, kp_c = tid & 15;
;     const int vp_row0 = tid >> 3, vp_c = tid & 7;
;     const bf16* ksrc = QK + 1024 + 2 * hp * 64 + kp_c * 8;
;     const bf16* vsrc = Vt + (size_t)(2 * hp * 64 + vp_row0) * TOK + vcol0 + vp_c * 8;
;     u32x4 kr0, kr1, vr0, vr1;
;     {
;         const int kv0 = 64 * kt_lo;
;         kr0 = *(const GAS u32x4*)(ksrc + (tok0 + (size_t)(kv0 + kp_row0) * dil) * 2048);
;         kr1 = *(const GAS u32x4*)(ksrc + (tok0 + (size_t)(kv0 + kp_row0 + 32) * dil) * 2048);
;         vr0 = *(const GAS u32x4*)(vsrc + kv0);
;         vr1 = *(const GAS u32x4*)(vsrc + (size_t)64 * TOK + kv0);
;         LAS unsigned char* kb = lds; LAS unsigned char* vb = lds + AT_KBYTES;
;         *(LAS u32x4*)(kb + kp_row0 * AT_KROW + kp_c * 16) = kr0; *(LAS u32x4*)(kb + (kp_row0 + 32) * AT_KROW + kp_c * 16) = kr1;
;         { LAS unsigned char* p0 = vb + vp_row0 * AT_VROW + vp_c * 16; LAS unsigned char* p1 = vb + (vp_row0 + 64) * AT_VROW + vp_c * 16;
;           *(LAS u32x2*)p0 = (u32x2){vr0.x, vr0.y}; *(LAS u32x2*)(p0 + 8) = (u32x2){vr0.z, vr0.w}; *(LAS u32x2*)p1 = (u32x2){vr1.x, vr1.y}; *(LAS u32x2*)(p1 + 8) = (u32x2){vr1.z, vr1.w}; }
.LBB0_378:
	s_lshr_b32 s0, s16, 2
	s_mov_b32 s1, s17
	s_or_b32 s17, s0, s48
	s_waitcnt vmcnt(0)
	v_mov_b32_e32 v3, v206
	s_cmp_eq_u32 s17, s1
	s_nop 0
	v_readfirstlane_b32 s22, v3
	s_cbranch_scc1 .LBB0_380
	s_lshl_b32 s1, s17, 1
	v_ashrrev_i32_e32 v0, 11, v3
	v_add_u32_e32 v4, s1, v0
	v_ashrrev_i32_e32 v5, 31, v4
	v_lshlrev_b64 v[4:5], 13, v[4:5]
	v_and_b32_e32 v0, 0x7ff, v3
	v_lshl_add_u64 v[4:5], s[82:83], 0, v[4:5]
	v_lshlrev_b32_e32 v0, 2, v0
	v_lshl_add_u64 v[4:5], v[4:5], 0, v[0:1]
	v_add_u32_e32 v6, 0x200, v3
	global_load_dword v2, v[4:5], off
	v_ashrrev_i32_e32 v4, 11, v6
	v_add_u32_e32 v4, s1, v4
	v_ashrrev_i32_e32 v5, 31, v4
	v_lshlrev_b64 v[4:5], 13, v[4:5]
	v_and_b32_e32 v6, 0x7ff, v6
	v_lshl_add_u64 v[4:5], s[82:83], 0, v[4:5]
	v_lshlrev_b32_e32 v6, 2, v6
	v_mov_b32_e32 v7, v1
	v_lshl_add_u64 v[4:5], v[4:5], 0, v[6:7]
	v_add_u32_e32 v6, 0x400, v3
	global_load_dword v8, v[4:5], off
	v_ashrrev_i32_e32 v4, 11, v6
	v_add_u32_e32 v4, s1, v4
	v_ashrrev_i32_e32 v5, 31, v4
	v_lshlrev_b64 v[4:5], 13, v[4:5]
	v_and_b32_e32 v6, 0x7ff, v6
	v_lshl_add_u64 v[4:5], s[82:83], 0, v[4:5]
	v_lshlrev_b32_e32 v6, 2, v6
	v_lshl_add_u64 v[4:5], v[4:5], 0, v[6:7]
	v_add_u32_e32 v6, 0x600, v3
	global_load_dword v9, v[4:5], off
	v_ashrrev_i32_e32 v4, 11, v6
	v_add_u32_e32 v4, s1, v4
	v_ashrrev_i32_e32 v5, 31, v4
	v_lshlrev_b64 v[4:5], 13, v[4:5]
	v_and_b32_e32 v6, 0x7ff, v6
	v_lshl_add_u64 v[4:5], s[82:83], 0, v[4:5]
	v_lshlrev_b32_e32 v6, 2, v6
	v_lshl_add_u64 v[4:5], v[4:5], 0, v[6:7]
	global_load_dword v6, v[4:5], off
	v_add_u32_e32 v4, 0x800, v3
	v_ashrrev_i32_e32 v4, 11, v4
	v_add_u32_e32 v4, s1, v4
	v_ashrrev_i32_e32 v5, 31, v4
	v_lshlrev_b64 v[4:5], 13, v[4:5]
	v_lshl_add_u64 v[4:5], s[82:83], 0, v[4:5]
	v_lshl_add_u64 v[4:5], v[4:5], 0, v[0:1]
	v_add_u32_e32 v0, 0xa00, v3
	global_load_dword v7, v[4:5], off
	v_ashrrev_i32_e32 v4, 11, v0
	v_add_u32_e32 v4, s1, v4
	v_ashrrev_i32_e32 v5, 31, v4
	v_lshlrev_b64 v[4:5], 13, v[4:5]
	v_and_b32_e32 v0, 0x7ff, v0
	v_lshl_add_u64 v[4:5], s[82:83], 0, v[4:5]
	v_lshlrev_b32_e32 v0, 2, v0
	v_lshl_add_u64 v[4:5], v[4:5], 0, v[0:1]
	v_add_u32_e32 v0, 0xc00, v3
	global_load_dword v10, v[4:5], off
	v_ashrrev_i32_e32 v4, 11, v0
	v_add_u32_e32 v4, s1, v4
	v_ashrrev_i32_e32 v5, 31, v4
	v_lshlrev_b64 v[4:5], 13, v[4:5]
	v_and_b32_e32 v0, 0x7ff, v0
	v_lshl_add_u64 v[4:5], s[82:83], 0, v[4:5]
	v_lshlrev_b32_e32 v0, 2, v0
	v_lshl_add_u64 v[4:5], v[4:5], 0, v[0:1]
	v_add_u32_e32 v0, 0xe00, v3
	global_load_dword v11, v[4:5], off
	v_ashrrev_i32_e32 v4, 11, v0
	v_add_u32_e32 v4, s1, v4
	v_ashrrev_i32_e32 v5, 31, v4
	v_lshlrev_b64 v[4:5], 13, v[4:5]
	v_and_b32_e32 v0, 0x7ff, v0
	v_lshl_add_u64 v[4:5], s[82:83], 0, v[4:5]
	v_lshlrev_b32_e32 v0, 2, v0
	v_lshl_add_u64 v[4:5], v[4:5], 0, v[0:1]
	global_load_dword v0, v[4:5], off
	v_lshl_add_u32 v4, v3, 2, 0
	v_add_u32_e32 v4, 0x11800, v4
	s_waitcnt vmcnt(6)
	ds_write2st64_b32 v4, v2, v8 offset1:8
	s_waitcnt vmcnt(4)
	ds_write2st64_b32 v4, v9, v6 offset0:16 offset1:24
	s_waitcnt vmcnt(2)
	ds_write2st64_b32 v4, v7, v10 offset0:32 offset1:40
	s_waitcnt vmcnt(0)
	ds_write2st64_b32 v4, v11, v0 offset0:48 offset1:56
.LBB0_380:
	s_and_b32 s4, s16, 3
	s_or_b32 s4, s4, s42
	s_lshl_b32 s4, s4, 3
	s_add_i32 s4, s4, s43
	s_bfe_u32 s20, s22, 0x20006
	s_ashr_i32 s12, s4, 3
	s_lshl_b32 s14, s20, 5
	v_and_b32_e32 v190, 31, v3
	s_ashr_i32 s13, s12, 31
	s_or_b32 s24, s14, s33
	s_ashr_i32 s21, s22, 8
	s_lshl_b64 s[4:5], s[12:13], 11
	v_or_b32_e32 v193, s24, v190
	v_or_b32_e32 v134, s4, v193
	v_mov_b32_e32 v135, s5
	s_lshl_b32 s18, s17, 7
	s_lshl_b32 s8, s21, 6
	v_lshlrev_b64 v[4:5], 12, v[134:135]
	s_add_i32 s8, s8, s18
	v_bfe_u32 v191, v3, 5, 1
	v_lshl_add_u64 v[4:5], s[40:41], 0, v[4:5]
	s_ashr_i32 s9, s8, 31
	v_lshl_add_u64 v[4:5], s[8:9], 1, v[4:5]
	v_lshlrev_b32_e32 v136, 4, v191
	v_mov_b32_e32 v137, v1
	s_lshl_b32 s0, s0, 7
	v_lshl_add_u64 v[4:5], v[4:5], 0, v[136:137]
	v_ashrrev_i32_e32 v0, 3, v3
	s_add_i32 s80, s49, s0
	global_load_dwordx4 v[124:127], v[4:5], off
	global_load_dwordx4 v[120:123], v[4:5], off offset:32
	global_load_dwordx4 v[116:119], v[4:5], off offset:64
	global_load_dwordx4 v[112:115], v[4:5], off offset:96
	v_add_u32_e32 v4, s18, v0
	s_lshl_b64 s[0:1], s[80:81], 1
	s_lshr_b32 s19, s22, 6
	s_lshl_b32 s8, s17, 8
	v_ashrrev_i32_e32 v5, 31, v4
	s_add_u32 s10, s61, s8
	v_lshlrev_b64 v[4:5], 17, v[4:5]
	v_and_b32_e32 v194, 63, v3
	v_ashrrev_i32_e32 v2, 4, v3
	s_addc_u32 s11, s2, 0
	v_lshlrev_b32_e32 v3, 4, v3
	v_lshl_add_u64 v[4:5], s[64:65], 0, v[4:5]
	s_lshl_b64 s[8:9], s[12:13], 12
	v_and_b32_e32 v138, 0xf0, v3
	v_lshl_add_u64 v[4:5], v[4:5], 0, s[8:9]
	v_and_b32_e32 v140, 0x70, v3
	v_mov_b32_e32 v141, v1
	v_ashrrev_i32_e32 v3, 31, v2
	v_add_u32_e32 v10, 32, v2
	v_mov_b32_e32 v139, v1
	v_lshl_add_u64 v[16:17], v[4:5], 0, v[140:141]
	v_lshl_add_u64 v[4:5], s[4:5], 0, v[2:3]
	v_ashrrev_i32_e32 v11, 31, v10
	v_lshl_add_u64 v[8:9], s[10:11], 0, v[138:139]
	v_lshlrev_b64 v[4:5], 12, v[4:5]
	v_lshl_add_u64 v[10:11], s[4:5], 0, v[10:11]
	v_lshl_add_u64 v[4:5], v[8:9], 0, v[4:5]
	v_lshlrev_b64 v[10:11], 12, v[10:11]
	global_load_dwordx4 v[4:7], v[4:5], off
	v_lshl_add_u64 v[8:9], v[8:9], 0, v[10:11]
	global_load_dwordx4 v[8:11], v[8:9], off
	s_nop 0
	global_load_dwordx4 v[12:15], v[16:17], off
	v_add_co_u32_e32 v16, vcc, s87, v16
	v_mul_lo_u32 v137, v2, s50
	s_nop 0
	v_addc_co_u32_e32 v17, vcc, 0, v17, vcc
	global_load_dwordx4 v[16:19], v[16:17], off
	v_add3_u32 v20, 0, v137, v138
	v_mul_u32_u24_e32 v196, 0x90, v0
	v_lshlrev_b32_e32 v217, 2, v191
	s_lshl_b32 s15, s21, 13
	s_lshl_b64 s[12:13], s[12:13], 23
	v_lshlrev_b64 v[2:3], 12, v[2:3]
	s_add_i32 s15, s15, 0
	v_lshl_add_u64 v[2:3], s[12:13], 0, v[2:3]
	s_add_i32 s23, s15, 0x11800
	s_add_i32 s15, s15, 0x11714
	v_or_b32_e32 v2, v2, v138
	v_lshl_add_u64 v[144:145], v[2:3], 0, s[0:1]
	v_mov_b32_e32 v2, v1
	v_mov_b32_e32 v3, v1
	v_lshlrev_b32_e32 v192, 4, v191
	s_mov_b32 s25, 0
	v_add_u32_e32 v195, 0x2200, v137
	s_or_b32 s26, s24, 31
	v_mul_u32_u24_e32 v197, 0x110, v190
	s_lshl_b32 s27, s21, 7
	v_mul_u32_u24_e32 v141, 0x90, v190
	v_mov_b32_e32 v139, 0
	v_mov_b32_e32 v198, 0xf149f2ca
	s_waitcnt vmcnt(3)
; #define LAS __attribute__((address_space(3)))
; template <int MODE> ...
;     ...
;         LAS unsigned char* kb = lds; LAS unsigned char* vb = lds + AT_KBYTES;
;         *(LAS u32x4*)(kb + kp_row0 * AT_KROW + kp_c * 16) = kr0; *(LAS u32x4*)(kb + (kp_row0 + 32) * AT_KROW + kp_c * 16) = kr1;
;         { LAS unsigned char* p0 = vb + vp_row0 * AT_VROW + vp_c * 16; LAS unsigned char* p1 = vb + (vp_row0 + 64) * AT_VROW + vp_c * 16;
;           *(LAS u32x2*)p0 = (u32x2){vr0.x, vr0.y}; *(LAS u32x2*)(p0 + 8) = (u32x2){vr0.z, vr0.w}; *(LAS u32x2*)p1 = (u32x2){vr1.x, vr1.y}; *(LAS u32x2*)(p1 + 8) = (u32x2){vr1.z, vr1.w}; }
;     }
;     f32x16 acc[NDV];
; #pragma unroll
;     for (int i = 0; i < NDV; ++i)
; #pragma unroll
;         for (int r = 0; r < 16; ++r) acc[i][r] = 0.f;
;     float mrun = -1e30f, lsum = 0.f;
	ds_write_b128 v20, v[4:7]
	v_and_b32_e32 v229, 0x60, v140
	v_bfe_u32 v212, v140, 4, 1
	v_lshl_or_b32 v229, v212, 3, v229
	v_add3_u32 v4, 0, v196, v229
	v_add_u32_e32 v5, 0x4400, v4
	v_add_u32_e32 v4, 0x6800, v4
	s_waitcnt vmcnt(2)
	ds_write_b128 v20, v[8:11] offset:8704
	s_waitcnt vmcnt(1)
	ds_write2_b64 v5, v[12:13], v[14:15] offset1:2
	s_waitcnt vmcnt(0)
	ds_write2_b64 v4, v[16:17], v[18:19] offset1:2
	v_add_u32_e32 v4, s80, v0
	v_or_b32_e32 v0, s14, v190
	s_add_i32 s14, s33, s14
	v_ashrrev_i32_e32 v5, 31, v4
	v_sub_u32_e32 v199, v0, v217
	v_add_u32_e32 v0, s14, v190
	v_lshlrev_b64 v[4:5], 17, v[4:5]
	v_sub_u32_e32 v0, v0, v217
	v_mov_b32_e32 v14, v1
	v_mov_b32_e32 v15, v1
	v_lshl_add_u64 v[142:143], v[4:5], 0, s[8:9]
	v_lshl_add_u32 v200, v0, 2, s15
	v_mov_b32_e32 v0, v1
	v_mov_b32_e32 v4, v1
	v_mov_b32_e32 v5, v1
	v_mov_b32_e32 v6, v1
	v_mov_b32_e32 v7, v1
	v_mov_b32_e32 v8, v1
	v_mov_b32_e32 v9, v1
	v_mov_b32_e32 v10, v1
	v_mov_b32_e32 v11, v1
	v_mov_b32_e32 v12, v1
	v_mov_b32_e32 v13, v1
	v_mov_b64_e32 v[30:31], v[14:15]
	v_mov_b64_e32 v[46:47], v[14:15]
	v_mov_b64_e32 v[62:63], v[14:15]
	v_mov_b64_e32 v[78:79], v[14:15]
	v_or_b32_e32 v142, v142, v140
	s_movk_i32 s14, 0xffc0
	v_mov_b64_e32 v[28:29], v[12:13]
	v_mov_b64_e32 v[26:27], v[10:11]
	v_mov_b64_e32 v[24:25], v[8:9]
	v_mov_b64_e32 v[22:23], v[6:7]
	v_mov_b64_e32 v[20:21], v[4:5]
	v_mov_b64_e32 v[18:19], v[2:3]
	v_mov_b64_e32 v[16:17], v[0:1]
	v_mov_b64_e32 v[44:45], v[12:13]
	v_mov_b64_e32 v[42:43], v[10:11]
	v_mov_b64_e32 v[40:41], v[8:9]
	v_mov_b64_e32 v[38:39], v[6:7]
	v_mov_b64_e32 v[36:37], v[4:5]
	v_mov_b64_e32 v[34:35], v[2:3]
	v_mov_b64_e32 v[32:33], v[0:1]
	v_mov_b64_e32 v[60:61], v[12:13]
	v_mov_b64_e32 v[58:59], v[10:11]
	v_mov_b64_e32 v[56:57], v[8:9]
	v_mov_b64_e32 v[54:55], v[6:7]
	v_mov_b64_e32 v[52:53], v[4:5]
	v_mov_b64_e32 v[50:51], v[2:3]
	v_mov_b64_e32 v[48:49], v[0:1]
	v_mov_b64_e32 v[76:77], v[12:13]
	v_mov_b64_e32 v[74:75], v[10:11]
	v_mov_b64_e32 v[72:73], v[8:9]
	v_mov_b64_e32 v[70:71], v[6:7]
	v_mov_b64_e32 v[68:69], v[4:5]
	v_mov_b64_e32 v[66:67], v[2:3]
	v_mov_b64_e32 v[64:65], v[0:1]
; template <int MODE> ...
;     ...
;     for (int kt = kt_lo; kt <= kt_hi; ++kt) {
;         const int bufsel = (kt - kt_lo) & 1;
;         __syncthreads();
;         const bool more = kt < kt_hi;
;         if (more) {
;             const int kv1 = 64 * (kt + 1);
;             kr0 = *(const GAS u32x4*)(ksrc + (tok0 + (size_t)(kv1 + kp_row0) * dil) * 2048);
;             kr1 = *(const GAS u32x4*)(ksrc + (tok0 + (size_t)(kv1 + kp_row0 + 32) * dil) * 2048);
;             vr0 = *(const GAS u32x4*)(vsrc + kv1);
;             vr1 = *(const GAS u32x4*)(vsrc + (size_t)64 * TOK + kv1);
;             asm volatile("" ::: "memory");
;         }
;         const int kv0 = 64 * kt;
;         bool skip = kv0 > q_lo + 31;
;         if (MODE == 1) skip = skip || (kv0 + 63 < q_lo - 128);
;         if (!skip) {
;             const LAS unsigned char* kb = lds + bufsel * AT_BUF; const LAS unsigned char* vb = kb + AT_KBYTES;
;             f32x16 s0, s1;
; #pragma unroll
;             for (int r = 0; r < 16; ++r) { s0[r] = 0.f; s1[r] = 0.f; }
;             {
;                 bf16x8 ka[4], kc[4];
; #pragma unroll
;                 for (int ds = 0; ds < 4; ++ds) {
;                     ka[ds] = *(const LAS bf16x8*)(kb + r32 * AT_KROW + mp * 128 + (16 * ds + 8 * hi) * 2);
;                     kc[ds] = *(const LAS bf16x8*)(kb + (32 + r32) * AT_KROW + mp * 128 + (16 * ds + 8 * hi) * 2);
;                 }
;                 __builtin_amdgcn_sched_barrier(0);
; #pragma unroll
;                 for (int ds = 0; ds < 4; ++ds) {
;                     s0 = __builtin_amdgcn_mfma_f32_32x32x16_bf16(ka[ds], qf[ds], s0, 0, 0, 0);
;                     s1 = __builtin_amdgcn_mfma_f32_32x32x16_bf16(kc[ds], qf[ds], s1, 0, 0, 0);
;                 }
;             }
;             const int relbase = qi - kv0 - 4 * hi;
;             constexpr int cmax = (MODE == 0) ? 2047 : 128;
;             float mx = -1e30f;
;             bool interior = (kv0 + 63 <= q_lo);
;             if (MODE == 1) interior = interior && (q_lo + 31 - kv0 <= 128);
;             if (interior) {
;                 const LAS float* p = biasL + mp * 2048 + (relbase - 59);
; #pragma unroll
;                 for (int r = 0; r < 16; ++r) {
;                     const int o = 59 - ((r & 3) + 8 * (r >> 2));
;                     s0[r] += p[o]; s1[r] += p[o - 32];
;                     mx = fmaxf(mx, fmaxf(s0[r], s1[r]));
;                 }
.LBB0_381:
	v_lshl_add_u64 v[2:3], s[54:55], 0, v[144:145]
	v_add_co_u32_e32 v4, vcc, s90, v2
	v_lshl_add_u64 v[10:11], s[54:55], 0, v[142:143]
	s_nop 0
	v_addc_co_u32_e32 v5, vcc, 0, v3, vcc
	v_add_co_u32_e32 v6, vcc, s91, v2
	s_waitcnt lgkmcnt(0)
	s_nop 0
	v_addc_co_u32_e32 v7, vcc, 0, v3, vcc
	v_add_co_u32_e32 v12, vcc, 0x20000000, v10
	s_barrier
	s_nop 0
	v_addc_co_u32_e32 v13, vcc, 0, v11, vcc
	v_add_co_u32_e32 v14, vcc, 0x20800000, v10
	global_load_dwordx4 v[2:5], v[4:5], off offset:2048
	s_nop 0
	global_load_dwordx4 v[6:9], v[6:7], off offset:2048
	v_addc_co_u32_e32 v15, vcc, 0, v11, vcc
	global_load_dwordx4 v[10:13], v[12:13], off offset:128
	s_nop 0
	global_load_dwordx4 v[128:131], v[14:15], off offset:128
	s_and_b32 s29, s25, 1
	s_add_i32 s28, s14, 64
	s_cmp_gt_u32 s28, s26
	s_cbranch_scc1 .LBB0_387
	s_mul_i32 s15, s29, 0x8c00
	s_add_i32 s30, s15, 0
	s_add_i32 s15, s27, s30
	v_add3_u32 v0, s15, v197, v136
	ds_read_b128 v[80:83], v0
	ds_read_b128 v[148:151], v0 offset:32
	ds_read_b128 v[84:87], v0 offset:8704
	ds_read_b128 v[152:155], v0 offset:8736
	ds_read_b128 v[156:159], v0 offset:64
	ds_read_b128 v[160:163], v0 offset:96
	ds_read_b128 v[164:167], v0 offset:8768
	ds_read_b128 v[168:171], v0 offset:8800
	ds_read2_b32 v[14:15], v200 offset0:58 offset1:59
	ds_read2_b32 v[218:219], v200 offset0:26 offset1:27
	ds_read2_b32 v[220:221], v200 offset0:24 offset1:25
	ds_read2_b32 v[222:223], v200 offset0:56 offset1:57
	ds_read2_b32 v[224:225], v200 offset0:50 offset1:51
	ds_read2_b32 v[174:175], v200 offset0:18 offset1:19
	ds_read2_b32 v[226:227], v200 offset0:48 offset1:49
	s_waitcnt lgkmcnt(14)
	v_mfma_f32_32x32x16_bf16 v[96:111], v[80:83], v[124:127], 0
	s_add_i32 s31, s14, 0x7f
	s_mov_b64 s[14:15], -1
	s_cmp_gt_u32 s31, s24
	ds_read2_b32 v[172:173], v200 offset0:16 offset1:17
	s_waitcnt lgkmcnt(13)
	v_mfma_f32_32x32x16_bf16 v[80:95], v[84:87], v[124:127], 0
	v_mfma_f32_32x32x16_bf16 v[96:111], v[148:151], v[120:123], v[96:111]
	ds_read2_b32 v[242:243], v200 offset0:42 offset1:43
	ds_read2_b32 v[182:183], v200 offset0:10 offset1:11
	s_waitcnt lgkmcnt(14)
	v_mfma_f32_32x32x16_bf16 v[80:95], v[152:155], v[120:123], v[80:95]
	ds_read2_b32 v[176:177], v200 offset0:40 offset1:41
	s_waitcnt lgkmcnt(14)
	v_mfma_f32_32x32x16_bf16 v[96:111], v[156:159], v[116:119], v[96:111]
	ds_read2_b32 v[184:185], v200 offset0:8 offset1:9
	s_waitcnt lgkmcnt(13)
	v_mfma_f32_32x32x16_bf16 v[80:95], v[164:167], v[116:119], v[80:95]
	v_mfma_f32_32x32x16_bf16 v[96:111], v[160:163], v[112:115], v[96:111]
	ds_read2_b32 v[180:181], v200 offset0:34 offset1:35
	ds_read2_b32 v[188:189], v200 offset0:2 offset1:3
	s_waitcnt lgkmcnt(14)
	v_mfma_f32_32x32x16_bf16 v[80:95], v[168:171], v[112:115], v[80:95]
	ds_read2_b32 v[178:179], v200 offset0:32 offset1:33
	s_nop 11
	s_cbranch_scc1 .LdaA_bias_masked
	s_waitcnt lgkmcnt(14)
	v_pk_add_f32 v[14:15], v[96:97], v[14:15] op_sel:[0,1] op_sel_hi:[1,0]
	ds_read2_b32 v[186:187], v200 offset0:0 offset1:1
	s_waitcnt lgkmcnt(14)
	v_pk_add_f32 v[166:167], v[80:81], v[218:219] op_sel:[0,1] op_sel_hi:[1,0]
	s_waitcnt lgkmcnt(13)
	v_pk_add_f32 v[168:169], v[82:83], v[220:221] op_sel:[0,1] op_sel_hi:[1,0]
	s_waitcnt lgkmcnt(12)
	v_pk_add_f32 v[148:149], v[98:99], v[222:223] op_sel:[0,1] op_sel_hi:[1,0]
	s_waitcnt lgkmcnt(11)
	v_pk_add_f32 v[152:153], v[100:101], v[224:225] op_sel:[0,1] op_sel_hi:[1,0]
	s_waitcnt lgkmcnt(10)
	v_pk_add_f32 v[174:175], v[84:85], v[174:175] op_sel:[0,1] op_sel_hi:[1,0]
	s_waitcnt lgkmcnt(9)
	v_pk_add_f32 v[150:151], v[102:103], v[226:227] op_sel:[0,1] op_sel_hi:[1,0]
	s_waitcnt lgkmcnt(8)
	v_pk_add_f32 v[172:173], v[86:87], v[172:173] op_sel:[0,1] op_sel_hi:[1,0]
	s_waitcnt lgkmcnt(7)
	v_pk_add_f32 v[170:171], v[104:105], v[242:243] op_sel:[0,1] op_sel_hi:[1,0]
	s_waitcnt lgkmcnt(6)
	v_pk_add_f32 v[182:183], v[88:89], v[182:183] op_sel:[0,1] op_sel_hi:[1,0]
	s_waitcnt lgkmcnt(5)
	v_pk_add_f32 v[176:177], v[106:107], v[176:177] op_sel:[0,1] op_sel_hi:[1,0]
	s_waitcnt lgkmcnt(4)
	v_pk_add_f32 v[184:185], v[90:91], v[184:185] op_sel:[0,1] op_sel_hi:[1,0]
	s_waitcnt lgkmcnt(3)
	v_pk_add_f32 v[180:181], v[108:109], v[180:181] op_sel:[0,1] op_sel_hi:[1,0]
	s_waitcnt lgkmcnt(2)
	v_pk_add_f32 v[188:189], v[92:93], v[188:189] op_sel:[0,1] op_sel_hi:[1,0]
	s_waitcnt lgkmcnt(1)
	v_pk_add_f32 v[178:179], v[110:111], v[178:179] op_sel:[0,1] op_sel_hi:[1,0]
	s_waitcnt lgkmcnt(0)
	v_pk_add_f32 v[186:187], v[94:95], v[186:187] op_sel:[0,1] op_sel_hi:[1,0]
	v_max_f32_e32 v80, v14, v166
	v_max_f32_e32 v81, v15, v167
	v_max3_f32 v82, v80, s84, v81
	v_max_f32_e32 v80, v168, v148
	v_max_f32_e32 v81, v169, v149
	v_max3_f32 v82, v82, v80, v81
	v_max_f32_e32 v80, v152, v174
	v_max_f32_e32 v81, v153, v175
	v_max3_f32 v82, v82, v80, v81
	v_max_f32_e32 v80, v150, v172
	v_max_f32_e32 v81, v151, v173
	v_max3_f32 v82, v82, v80, v81
	v_max_f32_e32 v80, v170, v182
	v_max_f32_e32 v81, v171, v183
	v_max3_f32 v82, v82, v80, v81
	v_max_f32_e32 v80, v176, v184
	v_max_f32_e32 v81, v177, v185
	v_max3_f32 v82, v82, v80, v81
	v_max_f32_e32 v80, v180, v188
	v_max_f32_e32 v81, v181, v189
	v_max3_f32 v82, v82, v80, v81
	v_max_f32_e32 v80, v178, v186
	v_max_f32_e32 v81, v179, v187
	v_max3_f32 v0, v82, v80, v81
	s_branch .LBB0_386

; __device__ __forceinline__ unsigned cvt_pk_bf16(float lo, float hi) { f32x2_t v = {lo, hi}; bf16x2_t b = __builtin_convertvector(v, bf16x2_t); return __builtin_bit_cast(unsigned, b); }
; __device__ __forceinline__ float fast_exp2(float x) { return __builtin_amdgcn_exp2f(x); }
; template <int MODE> ...
;     ...
;             const float mnew = fmaxf(mrun, mx);
;             const float alpha = fast_exp2(mrun - mnew);
;             mrun = mnew;
;             float ps = 0.f;
; #pragma unroll
;             for (int r = 0; r < 16; ++r) { s0[r] = fast_exp2(s0[r] - mnew); s1[r] = fast_exp2(s1[r] - mnew); ps += s0[r] + s1[r]; }
;             lsum = lsum * alpha + ps;
; #pragma unroll
;             for (int i = 0; i < NDV; ++i)
; #pragma unroll
;                 for (int r = 0; r < 16; ++r) acc[i][r] *= alpha;
;             bf16x8 pf[2][2];
; #pragma unroll
;             for (int t = 0; t < 2; ++t) {
;                 u32x4 w0, w1;
;                 w0.x = cvt_pk_bf16(s0[8 * t + 0], s0[8 * t + 1]); w0.y = cvt_pk_bf16(s0[8 * t + 2], s0[8 * t + 3]); w0.z = cvt_pk_bf16(s0[8 * t + 4], s0[8 * t + 5]); w0.w = cvt_pk_bf16(s0[8 * t + 6], s0[8 * t + 7]);
;                 w1.x = cvt_pk_bf16(s1[8 * t + 0], s1[8 * t + 1]); w1.y = cvt_pk_bf16(s1[8 * t + 2], s1[8 * t + 3]); w1.z = cvt_pk_bf16(s1[8 * t + 4], s1[8 * t + 5]); w1.w = cvt_pk_bf16(s1[8 * t + 6], s1[8 * t + 7]);
;                 pf[0][t] = __builtin_bit_cast(bf16x8, w0); pf[1][t] = __builtin_bit_cast(bf16x8, w1);
;             }
;     ...
;             {
;                 bf16x8 vcur[4], vnxt[4];
;                 AT_LOADV(vcur, 0);
.Lresc_keep_A:
	v_sub_f32_e32 v85, v152, v83
	v_exp_f32_e32 v152, v85
	v_sub_f32_e32 v85, v174, v83
	v_exp_f32_e32 v156, v85
	v_sub_f32_e32 v85, v153, v83
	v_exp_f32_e32 v88, v85
	v_sub_f32_e32 v85, v175, v83
	v_exp_f32_e32 v86, v85
	v_sub_f32_e32 v85, v150, v83
	v_exp_f32_e32 v150, v85
	v_sub_f32_e32 v85, v172, v83
	v_exp_f32_e32 v153, v85
	v_sub_f32_e32 v85, v151, v83
	v_exp_f32_e32 v92, v85
	v_sub_f32_e32 v85, v173, v83
	v_exp_f32_e32 v90, v85
	v_sub_f32_e32 v85, v170, v83
	v_exp_f32_e32 v151, v85
	v_sub_f32_e32 v85, v182, v83
	v_exp_f32_e32 v157, v85
	v_sub_f32_e32 v85, v171, v83
	v_exp_f32_e32 v96, v85
	v_sub_f32_e32 v85, v183, v83
	v_exp_f32_e32 v94, v85
	v_sub_f32_e32 v85, v176, v83
	v_exp_f32_e32 v158, v85
	v_sub_f32_e32 v85, v184, v83
	v_exp_f32_e32 v159, v85
	v_sub_f32_e32 v85, v177, v83
	v_sub_f32_e32 v0, v14, v83
	v_exp_f32_e32 v100, v85
	v_sub_f32_e32 v85, v185, v83
	v_exp_f32_e32 v110, v0
	v_sub_f32_e32 v0, v166, v83
	v_sub_f32_e32 v14, v167, v83
	v_exp_f32_e32 v98, v85
	v_sub_f32_e32 v85, v180, v83
	v_exp_f32_e32 v154, v0
	v_sub_f32_e32 v0, v15, v83
	v_exp_f32_e32 v80, v14
	v_sub_f32_e32 v14, v148, v83
	v_exp_f32_e32 v160, v85
	v_sub_f32_e32 v85, v188, v83
	v_exp_f32_e32 v0, v0
	v_exp_f32_e32 v111, v14
	v_sub_f32_e32 v14, v168, v83
	v_exp_f32_e32 v161, v85
	v_sub_f32_e32 v85, v181, v83
	v_exp_f32_e32 v155, v14
	v_sub_f32_e32 v14, v149, v83
	v_exp_f32_e32 v104, v85
	v_sub_f32_e32 v85, v189, v83
	v_exp_f32_e32 v84, v14
	v_sub_f32_e32 v14, v169, v83
	v_exp_f32_e32 v102, v85
	v_sub_f32_e32 v85, v178, v83
	v_add_f32_e32 v81, v154, v110
	v_exp_f32_e32 v14, v14
	v_exp_f32_e32 v162, v85
	v_sub_f32_e32 v85, v186, v83
	v_exp_f32_e32 v163, v85
	v_sub_f32_e32 v85, v179, v83
	v_pk_add_f32 v[108:109], v[80:81], v[0:1]
	v_exp_f32_e32 v148, v85
	v_sub_f32_e32 v85, v187, v83
	v_pk_add_f32 v[108:109], v[108:109], v[108:109] op_sel_hi:[0,1]
	v_add_f32_e32 v15, v155, v111
	v_exp_f32_e32 v106, v85
	v_mov_b32_e32 v85, v109
	v_pk_add_f32 v[108:109], v[14:15], v[84:85]
	v_add_f32_e32 v87, v156, v152
	v_pk_add_f32 v[108:109], v[108:109], v[108:109] op_sel_hi:[0,1]
	v_mov_b32_e32 v89, v109
	v_pk_add_f32 v[108:109], v[86:87], v[88:89]
	v_add_f32_e32 v91, v153, v150
	v_pk_add_f32 v[108:109], v[108:109], v[108:109] op_sel_hi:[0,1]
	v_mov_b32_e32 v93, v109
	v_pk_add_f32 v[108:109], v[90:91], v[92:93]
	v_add_f32_e32 v95, v157, v151
	v_pk_add_f32 v[108:109], v[108:109], v[108:109] op_sel_hi:[0,1]
	v_mov_b32_e32 v97, v109
	v_pk_add_f32 v[108:109], v[94:95], v[96:97]
	v_add_f32_e32 v99, v159, v158
	v_pk_add_f32 v[108:109], v[108:109], v[108:109] op_sel_hi:[0,1]
	v_mov_b32_e32 v101, v109
	v_pk_add_f32 v[108:109], v[98:99], v[100:101]
	v_add_f32_e32 v103, v161, v160
	v_pk_add_f32 v[108:109], v[108:109], v[108:109] op_sel_hi:[0,1]
	v_mov_b32_e32 v105, v109
	v_pk_add_f32 v[108:109], v[102:103], v[104:105]
	v_add_f32_e32 v107, v163, v162
	v_pk_add_f32 v[108:109], v[108:109], v[108:109] op_sel_hi:[0,1]
	v_mov_b32_e32 v149, v109
	v_pk_add_f32 v[108:109], v[106:107], v[148:149]
	v_cvt_pk_bf16_f32 v87, v153, v90
	v_add_f32_e32 v15, v108, v109
	v_cvt_pk_bf16_f32 v108, v110, v0
	v_add3_u32 v0, s30, v141, v192
	v_add_u32_e32 v0, 0x4000, v0
	v_cvt_pk_bf16_f32 v109, v111, v84
	v_cvt_pk_bf16_f32 v110, v152, v88
	v_cvt_pk_bf16_f32 v111, v150, v92
	v_cvt_pk_bf16_f32 v88, v151, v96
	v_cvt_pk_bf16_f32 v89, v158, v100
	v_cvt_pk_bf16_f32 v90, v160, v104
	v_cvt_pk_bf16_f32 v91, v162, v148
	v_cvt_pk_bf16_f32 v92, v157, v94
	v_cvt_pk_bf16_f32 v93, v159, v98
	v_cvt_pk_bf16_f32 v94, v161, v102
	v_cvt_pk_bf16_f32 v95, v163, v106
	ds_read_b128 v[96:99], v0 offset:1024
	ds_read_b128 v[100:103], v0 offset:1056
	ds_read_b128 v[104:107], v0 offset:1088
	ds_read_b128 v[148:151], v0 offset:1120
	v_add3_u32 v0, s30, v192, v141
	v_cvt_pk_bf16_f32 v85, v155, v14
	v_add_u32_e32 v14, 0x5000, v0
	v_cvt_pk_bf16_f32 v84, v154, v80
	v_cvt_pk_bf16_f32 v86, v156, v86
	ds_read_b128 v[152:155], v14 offset:1536
	ds_read_b128 v[156:159], v14 offset:1568
	ds_read_b128 v[160:163], v14 offset:1600
	ds_read_b128 v[164:167], v14 offset:1632
	v_sub_f32_e32 v82, v198, v83
	v_exp_f32_e32 v82, v82
	s_nop 0
	s_cmp_eq_u64 s[100:101], 0
	s_cbranch_scc1 .Lresc_skip_A
	v_pk_mul_f32 v[78:79], v[78:79], v[82:83] op_sel_hi:[1,0]
	v_pk_mul_f32 v[76:77], v[76:77], v[82:83] op_sel_hi:[1,0]
	v_pk_mul_f32 v[74:75], v[74:75], v[82:83] op_sel_hi:[1,0]
	v_pk_mul_f32 v[72:73], v[72:73], v[82:83] op_sel_hi:[1,0]
	v_pk_mul_f32 v[70:71], v[70:71], v[82:83] op_sel_hi:[1,0]
	v_pk_mul_f32 v[68:69], v[68:69], v[82:83] op_sel_hi:[1,0]
	v_pk_mul_f32 v[66:67], v[66:67], v[82:83] op_sel_hi:[1,0]
	v_pk_mul_f32 v[64:65], v[64:65], v[82:83] op_sel_hi:[1,0]
	v_pk_mul_f32 v[62:63], v[62:63], v[82:83] op_sel_hi:[1,0]
	v_pk_mul_f32 v[60:61], v[60:61], v[82:83] op_sel_hi:[1,0]
	v_pk_mul_f32 v[58:59], v[58:59], v[82:83] op_sel_hi:[1,0]
	v_pk_mul_f32 v[56:57], v[56:57], v[82:83] op_sel_hi:[1,0]
	v_pk_mul_f32 v[54:55], v[54:55], v[82:83] op_sel_hi:[1,0]
	v_pk_mul_f32 v[52:53], v[52:53], v[82:83] op_sel_hi:[1,0]
	v_pk_mul_f32 v[50:51], v[50:51], v[82:83] op_sel_hi:[1,0]
	v_pk_mul_f32 v[48:49], v[48:49], v[82:83] op_sel_hi:[1,0]
	v_pk_mul_f32 v[46:47], v[46:47], v[82:83] op_sel_hi:[1,0]
	v_pk_mul_f32 v[44:45], v[44:45], v[82:83] op_sel_hi:[1,0]
	v_pk_mul_f32 v[42:43], v[42:43], v[82:83] op_sel_hi:[1,0]
	v_pk_mul_f32 v[40:41], v[40:41], v[82:83] op_sel_hi:[1,0]
	v_pk_mul_f32 v[38:39], v[38:39], v[82:83] op_sel_hi:[1,0]
	v_pk_mul_f32 v[36:37], v[36:37], v[82:83] op_sel_hi:[1,0]
	v_pk_mul_f32 v[34:35], v[34:35], v[82:83] op_sel_hi:[1,0]
	v_pk_mul_f32 v[32:33], v[32:33], v[82:83] op_sel_hi:[1,0]
	v_pk_mul_f32 v[30:31], v[30:31], v[82:83] op_sel_hi:[1,0]
	v_pk_mul_f32 v[28:29], v[28:29], v[82:83] op_sel_hi:[1,0]
	v_pk_mul_f32 v[26:27], v[26:27], v[82:83] op_sel_hi:[1,0]
	v_pk_mul_f32 v[24:25], v[24:25], v[82:83] op_sel_hi:[1,0]
	v_pk_mul_f32 v[22:23], v[22:23], v[82:83] op_sel_hi:[1,0]
	v_pk_mul_f32 v[20:21], v[20:21], v[82:83] op_sel_hi:[1,0]
	v_pk_mul_f32 v[18:19], v[18:19], v[82:83] op_sel_hi:[1,0]
	v_pk_mul_f32 v[16:17], v[16:17], v[82:83] op_sel_hi:[1,0]
; #define LAS __attribute__((address_space(3)))
; template <int MODE> ...
;     ...
;             {
;                 bf16x8 vcur[4], vnxt[4];
;                 AT_LOADV(vcur, 0);
; #pragma unroll
;                 for (int dvb = 0; dvb < NDV; ++dvb) {
;                     if (dvb + 1 < NDV) AT_LOADV(vnxt, dvb + 1);
;                     __builtin_amdgcn_sched_barrier(0);
; #pragma unroll
;                     for (int i = 0; i < 4; ++i) acc[dvb] = __builtin_amdgcn_mfma_f32_32x32x16_bf16(vcur[i], pf[i >> 1][i & 1], acc[dvb], 0, 0, 0);
;                     __builtin_amdgcn_sched_barrier(0);
; #pragma unroll
;                     for (int i = 0; i < 4; ++i) vcur[i] = vnxt[i];
;                 }
;             }
;     ...
;         }
;         if (more) {
;             LAS unsigned char* kb = lds + (bufsel ^ 1) * AT_BUF; LAS unsigned char* vb = kb + AT_KBYTES;
;             *(LAS u32x4*)(kb + kp_row0 * AT_KROW + kp_c * 16) = kr0; *(LAS u32x4*)(kb + (kp_row0 + 32) * AT_KROW + kp_c * 16) = kr1;
;             { LAS unsigned char* p0 = vb + vp_row0 * AT_VROW + vp_c * 16; LAS unsigned char* p1 = vb + (vp_row0 + 64) * AT_VROW + vp_c * 16;
;           *(LAS u32x2*)p0 = (u32x2){vr0.x, vr0.y}; *(LAS u32x2*)(p0 + 8) = (u32x2){vr0.z, vr0.w}; *(LAS u32x2*)p1 = (u32x2){vr1.x, vr1.y}; *(LAS u32x2*)(p1 + 8) = (u32x2){vr1.z, vr1.w}; }
;         }
.Lresc_skip_A:
	s_waitcnt lgkmcnt(7)
	v_mfma_f32_32x32x16_bf16 v[64:79], v[96:99], v[108:111], v[64:79]
	s_waitcnt lgkmcnt(6)
	v_mfma_f32_32x32x16_bf16 v[64:79], v[100:103], v[88:91], v[64:79]
	s_waitcnt lgkmcnt(5)
	v_mfma_f32_32x32x16_bf16 v[64:79], v[104:107], v[84:87], v[64:79]
	s_waitcnt lgkmcnt(4)
	v_mfma_f32_32x32x16_bf16 v[64:79], v[148:151], v[92:95], v[64:79]
	v_add_u32_e32 v14, 0x6000, v0
	ds_read_b128 v[96:99], v14 offset:2048
	ds_read_b128 v[100:103], v14 offset:2080
	ds_read_b128 v[104:107], v14 offset:2112
	ds_read_b128 v[148:151], v14 offset:2144
	s_waitcnt lgkmcnt(7)
	v_mfma_f32_32x32x16_bf16 v[48:63], v[152:155], v[108:111], v[48:63]
	s_waitcnt lgkmcnt(6)
	v_mfma_f32_32x32x16_bf16 v[48:63], v[156:159], v[88:91], v[48:63]
	s_waitcnt lgkmcnt(5)
	v_mfma_f32_32x32x16_bf16 v[48:63], v[160:163], v[84:87], v[48:63]
	s_waitcnt lgkmcnt(4)
	v_mfma_f32_32x32x16_bf16 v[48:63], v[164:167], v[92:95], v[48:63]
	v_add_u32_e32 v0, 0x7000, v0
	ds_read_b128 v[152:155], v0 offset:2560
	ds_read_b128 v[156:159], v0 offset:2592
	ds_read_b128 v[160:163], v0 offset:2624
	ds_read_b128 v[164:167], v0 offset:2656
	s_waitcnt lgkmcnt(7)
	v_mfma_f32_32x32x16_bf16 v[32:47], v[96:99], v[108:111], v[32:47]
	s_waitcnt lgkmcnt(6)
	v_mfma_f32_32x32x16_bf16 v[32:47], v[100:103], v[88:91], v[32:47]
	s_waitcnt lgkmcnt(5)
	v_mfma_f32_32x32x16_bf16 v[32:47], v[104:107], v[84:87], v[32:47]
	s_waitcnt lgkmcnt(4)
	v_mfma_f32_32x32x16_bf16 v[32:47], v[148:151], v[92:95], v[32:47]
	s_waitcnt lgkmcnt(3)
	v_mfma_f32_32x32x16_bf16 v[16:31], v[152:155], v[108:111], v[16:31]
	s_waitcnt lgkmcnt(2)
	v_mfma_f32_32x32x16_bf16 v[16:31], v[156:159], v[88:91], v[16:31]
	s_waitcnt lgkmcnt(1)
	v_mfma_f32_32x32x16_bf16 v[16:31], v[160:163], v[84:87], v[16:31]
	s_waitcnt lgkmcnt(0)
	v_mfma_f32_32x32x16_bf16 v[16:31], v[164:167], v[92:95], v[16:31]
	v_fmac_f32_e32 v15, v139, v82
	v_mov_b32_e32 v198, v83
	v_mov_b32_e32 v139, v15
.LBB0_387:
	s_xor_b32 s14, s29, 1
	s_mul_i32 s14, s14, 0x8c00
	s_add_i32 s14, s14, 0
	v_add3_u32 v0, s14, v137, v138
	s_waitcnt vmcnt(3)
	ds_write_b128 v0, v[2:5]
	v_add3_u32 v0, s14, v195, v138
	s_waitcnt vmcnt(2)
	ds_write_b128 v0, v[6:9]
	v_add3_u32 v0, s14, v196, v229
	s_add_i32 s25, s25, 1
	v_add_u32_e32 v2, 0x4400, v0
	v_lshl_add_u64 v[142:143], v[142:143], 0, s[96:97]
	v_subrev_u32_e32 v199, 64, v199
	v_add_u32_e32 v200, 0xffffff00, v200
	s_cmp_eq_u32 s33, s28
	v_lshl_add_u64 v[144:145], v[144:145], 0, s[94:95]
	v_add_u32_e32 v0, 0x6800, v0
	s_waitcnt vmcnt(1)
	ds_write2_b64 v2, v[10:11], v[12:13] offset1:2
	s_waitcnt vmcnt(0)
	ds_write2_b64 v0, v[128:129], v[130:131] offset1:2
	s_cbranch_scc1 .LBB0_389
	s_mov_b32 s14, s28
	s_branch .LBB0_381
; #define LAS __attribute__((address_space(3)))
; template <int MODE> ...
;     ...
;         const int kv0 = 64 * kt;
;         bool skip = kv0 > q_lo + 31;
;         if (MODE == 1) skip = skip || (kv0 + 63 < q_lo - 128);
;         if (!skip) {
;             const LAS unsigned char* kb = lds + bufsel * AT_BUF; const LAS unsigned char* vb = kb + AT_KBYTES;
;             f32x16 s0, s1;
; #pragma unroll
;             for (int r = 0; r < 16; ++r) { s0[r] = 0.f; s1[r] = 0.f; }
;             {
;                 bf16x8 ka[4], kc[4];
; #pragma unroll
;                 for (int ds = 0; ds < 4; ++ds) {
;                     ka[ds] = *(const LAS bf16x8*)(kb + r32 * AT_KROW + mp * 128 + (16 * ds + 8 * hi) * 2);
;                     kc[ds] = *(const LAS bf16x8*)(kb + (32 + r32) * AT_KROW + mp * 128 + (16 * ds + 8 * hi) * 2);
;                 }
;                 __builtin_amdgcn_sched_barrier(0);
; #pragma unroll
;                 for (int ds = 0; ds < 4; ++ds) {
;                     s0 = __builtin_amdgcn_mfma_f32_32x32x16_bf16(ka[ds], qf[ds], s0, 0, 0, 0);
;                     s1 = __builtin_amdgcn_mfma_f32_32x32x16_bf16(kc[ds], qf[ds], s1, 0, 0, 0);
;                 }
;             }
;             const int relbase = qi - kv0 - 4 * hi;
;             constexpr int cmax = (MODE == 0) ? 2047 : 128;
;             float mx = -1e30f;
;             bool interior = (kv0 + 63 <= q_lo);
;             if (MODE == 1) interior = interior && (q_lo + 31 - kv0 <= 128);
;             if (interior) {
;                 const LAS float* p = biasL + mp * 2048 + (relbase - 59);
; #pragma unroll
;                 for (int r = 0; r < 16; ++r) {
;                     const int o = 59 - ((r & 3) + 8 * (r >> 2));
;                     s0[r] += p[o]; s1[r] += p[o - 32];
;                     mx = fmaxf(mx, fmaxf(s0[r], s1[r]));
;                 }
.LBB0_389:
	s_lshl_b32 s14, s25, 6
	s_cmp_gt_u32 s14, s26
	s_waitcnt lgkmcnt(0)
	s_barrier
	s_cbranch_scc1 .LBB0_395
	s_bitcmp1_b32 s25, 0
	s_cselect_b32 s15, 0x8c00, 0
	s_add_i32 s25, s15, 0
	s_add_i32 s27, s27, s25
	v_add3_u32 v0, s27, v197, v136
	ds_read_b128 v[2:5], v0
	ds_read_b128 v[6:9], v0 offset:32
	ds_read_b128 v[10:13], v0 offset:8704
	ds_read_b128 v[128:131], v0 offset:8736
	ds_read_b128 v[142:145], v0 offset:64
	ds_read_b128 v[148:151], v0 offset:96
	ds_read_b128 v[152:155], v0 offset:8768
	ds_read_b128 v[156:159], v0 offset:8800
	s_waitcnt lgkmcnt(7)
	v_mfma_f32_32x32x16_bf16 v[96:111], v[2:5], v[124:127], 0
	v_or_b32_e32 v0, s14, v217
	s_or_b32 s26, s14, 63
	v_sub_u32_e32 v0, v193, v0
	s_mov_b64 s[14:15], -1
	s_cmp_gt_u32 s26, s24
	s_waitcnt lgkmcnt(5)
	v_mfma_f32_32x32x16_bf16 v[80:95], v[10:13], v[124:127], 0
	v_mfma_f32_32x32x16_bf16 v[96:111], v[6:9], v[120:123], v[96:111]
	s_waitcnt lgkmcnt(4)
	v_mfma_f32_32x32x16_bf16 v[80:95], v[128:131], v[120:123], v[80:95]
	s_waitcnt lgkmcnt(3)
	v_mfma_f32_32x32x16_bf16 v[96:111], v[142:145], v[116:119], v[96:111]
	s_waitcnt lgkmcnt(1)
	v_mfma_f32_32x32x16_bf16 v[80:95], v[152:155], v[116:119], v[80:95]
	v_mfma_f32_32x32x16_bf16 v[96:111], v[148:151], v[112:115], v[96:111]
	s_waitcnt lgkmcnt(0)
	v_mfma_f32_32x32x16_bf16 v[80:95], v[156:159], v[112:115], v[80:95]
	s_cbranch_scc1 .LBB0_392
	v_lshl_add_u32 v118, v0, 2, s23
	v_add_u32_e32 v2, -4, v118
	v_add_u32_e32 v4, 0xffffff7c, v118
	ds_read2_b32 v[2:3], v2 offset1:1
	ds_read2_b32 v[4:5], v4 offset1:1
	v_add_u32_e32 v6, -12, v118
	v_add_u32_e32 v8, 0xffffff14, v118
	ds_read2_b32 v[6:7], v6 offset1:1
	ds_read2_b32 v[112:113], v8 offset1:1
	s_waitcnt lgkmcnt(3)
	v_pk_add_f32 v[116:117], v[96:97], v[2:3] op_sel:[0,1] op_sel_hi:[1,0]
	s_waitcnt lgkmcnt(2)
	v_pk_add_f32 v[128:129], v[80:81], v[4:5] op_sel:[0,1] op_sel_hi:[1,0]
	v_subrev_u32_e32 v4, 36, v118
	v_max_f32_e32 v2, v116, v128
	v_max_f32_e32 v3, v117, v129
	v_max3_f32 v12, v2, s84, v3
	v_add_u32_e32 v2, 0xffffff74, v118
	ds_read2_b32 v[2:3], v2 offset1:1
	s_waitcnt lgkmcnt(2)
	v_pk_add_f32 v[10:11], v[98:99], v[6:7] op_sel:[0,1] op_sel_hi:[1,0]
	v_add_u32_e32 v6, 0xffffff5c, v118
	v_subrev_u32_e32 v8, 44, v118
	ds_read2_b32 v[4:5], v4 offset1:1
	ds_read2_b32 v[6:7], v6 offset1:1
	ds_read2_b32 v[8:9], v8 offset1:1
	s_waitcnt lgkmcnt(3)
	v_pk_add_f32 v[136:137], v[82:83], v[2:3] op_sel:[0,1] op_sel_hi:[1,0]
	v_add_u32_e32 v13, 0xffffffb4, v118
	v_max_f32_e32 v2, v10, v136
	v_max_f32_e32 v3, v11, v137
	s_waitcnt lgkmcnt(2)
	v_pk_add_f32 v[14:15], v[100:101], v[4:5] op_sel:[0,1] op_sel_hi:[1,0]
	s_waitcnt lgkmcnt(1)
	v_pk_add_f32 v[124:125], v[84:85], v[6:7] op_sel:[0,1] op_sel_hi:[1,0]
	v_max3_f32 v2, v12, v2, v3
	v_max_f32_e32 v3, v14, v124
	v_max_f32_e32 v4, v15, v125
	v_max3_f32 v12, v2, v3, v4
	v_add_u32_e32 v2, 0xffffff54, v118
	ds_read2_b32 v[2:3], v2 offset1:1
	s_waitcnt lgkmcnt(1)
	v_pk_add_f32 v[6:7], v[102:103], v[8:9] op_sel:[0,1] op_sel_hi:[1,0]
	v_add_u32_e32 v4, 0xffffffbc, v118
	v_add_u32_e32 v8, 0xffffff3c, v118
	ds_read2_b32 v[4:5], v4 offset1:1
	ds_read2_b32 v[8:9], v8 offset1:1
	ds_read2_b32 v[114:115], v13 offset1:1
	s_waitcnt lgkmcnt(3)
	v_pk_add_f32 v[130:131], v[86:87], v[2:3] op_sel:[0,1] op_sel_hi:[1,0]
	s_mov_b64 s[14:15], 0
	v_max_f32_e32 v2, v6, v130
	v_max_f32_e32 v3, v7, v131
	v_max3_f32 v2, v12, v2, v3
	s_waitcnt lgkmcnt(2)
	v_pk_add_f32 v[12:13], v[104:105], v[4:5] op_sel:[0,1] op_sel_hi:[1,0]
	s_waitcnt lgkmcnt(1)
	v_pk_add_f32 v[122:123], v[88:89], v[8:9] op_sel:[0,1] op_sel_hi:[1,0]
	v_add_u32_e32 v8, 0xffffff9c, v118
	v_max_f32_e32 v3, v12, v122
	v_max_f32_e32 v4, v13, v123
	v_max3_f32 v120, v2, v3, v4
	v_add_u32_e32 v2, 0xffffff34, v118
	ds_read2_b32 v[2:3], v2 offset1:1
	s_waitcnt lgkmcnt(1)
	v_pk_add_f32 v[4:5], v[106:107], v[114:115] op_sel:[0,1] op_sel_hi:[1,0]
	v_add_u32_e32 v114, 0xffffff1c, v118
	v_add_u32_e32 v118, 0xffffff94, v118
	ds_read2_b32 v[8:9], v8 offset1:1
	ds_read2_b32 v[114:115], v114 offset1:1
	ds_read2_b32 v[118:119], v118 offset1:1
	s_waitcnt lgkmcnt(3)
	v_pk_add_f32 v[126:127], v[90:91], v[2:3] op_sel:[0,1] op_sel_hi:[1,0]
	s_waitcnt lgkmcnt(2)
	v_pk_add_f32 v[8:9], v[108:109], v[8:9] op_sel:[0,1] op_sel_hi:[1,0]
	v_max_f32_e32 v2, v4, v126
	v_max_f32_e32 v3, v5, v127
	v_max3_f32 v2, v120, v2, v3
	s_waitcnt lgkmcnt(1)
	v_pk_add_f32 v[120:121], v[92:93], v[114:115] op_sel:[0,1] op_sel_hi:[1,0]
	s_nop 0
	v_max_f32_e32 v3, v8, v120
	v_max_f32_e32 v114, v9, v121
	v_max3_f32 v114, v2, v3, v114
	s_waitcnt lgkmcnt(0)
	v_pk_add_f32 v[2:3], v[110:111], v[118:119] op_sel:[0,1] op_sel_hi:[1,0]
	v_pk_add_f32 v[118:119], v[94:95], v[112:113] op_sel:[0,1] op_sel_hi:[1,0]
	s_nop 0
	v_max_f32_e32 v112, v2, v118
	v_max_f32_e32 v113, v3, v119
	v_max3_f32 v138, v114, v112, v113

; __device__ __forceinline__ unsigned cvt_pk_bf16(float lo, float hi) { f32x2_t v = {lo, hi}; bf16x2_t b = __builtin_convertvector(v, bf16x2_t); return __builtin_bit_cast(unsigned, b); }
; __device__ __forceinline__ float max_x32(float v) { auto rr = __builtin_amdgcn_permlane32_swap(__float_as_uint(v), __float_as_uint(v), false, false); return fmaxf(__uint_as_float(rr[0]), __uint_as_float(rr[1])); }
; __device__ __forceinline__ float fast_exp2(float x) { return __builtin_amdgcn_exp2f(x); }
; template <int MODE> ...
;     ...
;             mx = max_x32(mx);
;             const float mnew = fmaxf(mrun, mx);
;             const float alpha = fast_exp2(mrun - mnew);
;             mrun = mnew;
;             float ps = 0.f;
; #pragma unroll
;             for (int r = 0; r < 16; ++r) { s0[r] = fast_exp2(s0[r] - mnew); s1[r] = fast_exp2(s1[r] - mnew); ps += s0[r] + s1[r]; }
;             lsum = lsum * alpha + ps;
; #pragma unroll
;             for (int i = 0; i < NDV; ++i)
; #pragma unroll
;                 for (int r = 0; r < 16; ++r) acc[i][r] *= alpha;
;             bf16x8 pf[2][2];
; #pragma unroll
;             for (int t = 0; t < 2; ++t) {
;                 u32x4 w0, w1;
;                 w0.x = cvt_pk_bf16(s0[8 * t + 0], s0[8 * t + 1]); w0.y = cvt_pk_bf16(s0[8 * t + 2], s0[8 * t + 3]); w0.z = cvt_pk_bf16(s0[8 * t + 4], s0[8 * t + 5]); w0.w = cvt_pk_bf16(s0[8 * t + 6], s0[8 * t + 7]);
;                 w1.x = cvt_pk_bf16(s1[8 * t + 0], s1[8 * t + 1]); w1.y = cvt_pk_bf16(s1[8 * t + 2], s1[8 * t + 3]); w1.z = cvt_pk_bf16(s1[8 * t + 4], s1[8 * t + 5]); w1.w = cvt_pk_bf16(s1[8 * t + 6], s1[8 * t + 7]);
;                 pf[0][t] = __builtin_bit_cast(bf16x8, w0); pf[1][t] = __builtin_bit_cast(bf16x8, w1);
;             }
;     ...
;             {
;                 bf16x8 vcur[4], vnxt[4];
;                 AT_LOADV(vcur, 0);
.LBB0_394:
	v_mov_b32_e32 v0, v138
	s_nop 1
	v_permlane32_swap_b32_e32 v138, v0
	s_nop 4
	v_max3_f32 v94, v198, v138, v0
	v_sub_f32_e32 v0, v116, v94
	v_exp_f32_e32 v98, v0
	v_sub_f32_e32 v0, v128, v94
	v_sub_f32_e32 v10, v10, v94
	v_sub_f32_e32 v6, v6, v94
	v_sub_f32_e32 v4, v4, v94
	v_exp_f32_e32 v102, v0
	v_sub_f32_e32 v0, v117, v94
	v_sub_f32_e32 v80, v129, v94
	v_exp_f32_e32 v99, v10
	v_sub_f32_e32 v10, v136, v94
	v_exp_f32_e32 v106, v6
	v_sub_f32_e32 v6, v130, v94
	v_exp_f32_e32 v110, v4
	v_sub_f32_e32 v4, v126, v94
	v_exp_f32_e32 v0, v0
	v_exp_f32_e32 v80, v80
	v_exp_f32_e32 v103, v10
	v_sub_f32_e32 v10, v11, v94
	v_sub_f32_e32 v11, v137, v94
	v_exp_f32_e32 v107, v6
	v_sub_f32_e32 v6, v7, v94
	v_sub_f32_e32 v7, v131, v94
	v_exp_f32_e32 v111, v4
	v_sub_f32_e32 v4, v5, v94
	v_sub_f32_e32 v5, v127, v94
	v_sub_f32_e32 v2, v2, v94
	v_exp_f32_e32 v82, v11
	v_sub_f32_e32 v11, v14, v94
	v_exp_f32_e32 v86, v7
	v_sub_f32_e32 v7, v12, v94
	v_exp_f32_e32 v90, v5
	v_sub_f32_e32 v5, v8, v94
	v_exp_f32_e32 v114, v2
	v_sub_f32_e32 v2, v118, v94
	v_exp_f32_e32 v104, v11
	v_sub_f32_e32 v11, v124, v94
	v_exp_f32_e32 v108, v7
	v_sub_f32_e32 v7, v122, v94
	v_exp_f32_e32 v112, v5
	v_sub_f32_e32 v5, v120, v94
	v_exp_f32_e32 v115, v2
	v_sub_f32_e32 v2, v3, v94
	v_sub_f32_e32 v96, v198, v94
	v_add_f32_e32 v81, v102, v98
	v_exp_f32_e32 v10, v10
	v_exp_f32_e32 v105, v11
	v_sub_f32_e32 v11, v15, v94
	v_exp_f32_e32 v109, v7
	v_sub_f32_e32 v7, v13, v94
	v_exp_f32_e32 v113, v5
	v_sub_f32_e32 v5, v9, v94
	v_exp_f32_e32 v100, v2
	v_sub_f32_e32 v2, v119, v94
	v_exp_f32_e32 v14, v11
	v_sub_f32_e32 v11, v125, v94
	v_exp_f32_e32 v12, v7
	v_sub_f32_e32 v7, v123, v94
	v_exp_f32_e32 v8, v5
	v_sub_f32_e32 v5, v121, v94
	v_exp_f32_e32 v94, v2
	v_exp_f32_e32 v2, v96
	v_pk_add_f32 v[96:97], v[80:81], v[0:1]
	v_add_f32_e32 v83, v103, v99
	v_pk_add_f32 v[96:97], v[96:97], v[96:97] op_sel_hi:[0,1]
	v_exp_f32_e32 v84, v11
	v_mov_b32_e32 v11, v97
	v_pk_add_f32 v[96:97], v[82:83], v[10:11]
	v_add_f32_e32 v85, v105, v104
	v_pk_add_f32 v[96:97], v[96:97], v[96:97] op_sel_hi:[0,1]
	v_exp_f32_e32 v6, v6
	v_mov_b32_e32 v15, v97
	v_pk_add_f32 v[96:97], v[84:85], v[14:15]
	v_add_f32_e32 v87, v107, v106
	v_pk_add_f32 v[96:97], v[96:97], v[96:97] op_sel_hi:[0,1]
	v_exp_f32_e32 v88, v7
	v_mov_b32_e32 v7, v97
	v_pk_add_f32 v[96:97], v[86:87], v[6:7]
	v_add_f32_e32 v89, v109, v108
	v_pk_add_f32 v[96:97], v[96:97], v[96:97] op_sel_hi:[0,1]
	v_exp_f32_e32 v4, v4
	v_mov_b32_e32 v13, v97
	v_pk_add_f32 v[96:97], v[88:89], v[12:13]
	v_add_f32_e32 v91, v111, v110
	v_pk_add_f32 v[96:97], v[96:97], v[96:97] op_sel_hi:[0,1]
	v_exp_f32_e32 v92, v5
	v_mov_b32_e32 v5, v97
	v_pk_add_f32 v[96:97], v[90:91], v[4:5]
	v_add_f32_e32 v93, v113, v112
	v_pk_add_f32 v[96:97], v[96:97], v[96:97] op_sel_hi:[0,1]
	v_mov_b32_e32 v9, v97
	v_pk_add_f32 v[96:97], v[92:93], v[8:9]
	v_add_f32_e32 v95, v115, v114
	v_pk_add_f32 v[96:97], v[96:97], v[96:97] op_sel_hi:[0,1]
	v_mov_b32_e32 v101, v97
	v_pk_add_f32 v[96:97], v[94:95], v[100:101]
	v_pk_mul_f32 v[78:79], v[78:79], v[2:3] op_sel_hi:[1,0]
	v_pk_mul_f32 v[76:77], v[76:77], v[2:3] op_sel_hi:[1,0]
	v_pk_mul_f32 v[74:75], v[74:75], v[2:3] op_sel_hi:[1,0]
	v_pk_mul_f32 v[72:73], v[72:73], v[2:3] op_sel_hi:[1,0]
	v_pk_mul_f32 v[70:71], v[70:71], v[2:3] op_sel_hi:[1,0]
	v_pk_mul_f32 v[68:69], v[68:69], v[2:3] op_sel_hi:[1,0]
	v_pk_mul_f32 v[66:67], v[66:67], v[2:3] op_sel_hi:[1,0]
	v_pk_mul_f32 v[64:65], v[64:65], v[2:3] op_sel_hi:[1,0]
	v_pk_mul_f32 v[62:63], v[62:63], v[2:3] op_sel_hi:[1,0]
	v_pk_mul_f32 v[60:61], v[60:61], v[2:3] op_sel_hi:[1,0]
	v_pk_mul_f32 v[58:59], v[58:59], v[2:3] op_sel_hi:[1,0]
	v_pk_mul_f32 v[56:57], v[56:57], v[2:3] op_sel_hi:[1,0]
	v_pk_mul_f32 v[54:55], v[54:55], v[2:3] op_sel_hi:[1,0]
	v_pk_mul_f32 v[52:53], v[52:53], v[2:3] op_sel_hi:[1,0]
	v_pk_mul_f32 v[50:51], v[50:51], v[2:3] op_sel_hi:[1,0]
	v_pk_mul_f32 v[48:49], v[48:49], v[2:3] op_sel_hi:[1,0]
	v_pk_mul_f32 v[46:47], v[46:47], v[2:3] op_sel_hi:[1,0]
	v_pk_mul_f32 v[44:45], v[44:45], v[2:3] op_sel_hi:[1,0]
	v_pk_mul_f32 v[42:43], v[42:43], v[2:3] op_sel_hi:[1,0]
	v_pk_mul_f32 v[40:41], v[40:41], v[2:3] op_sel_hi:[1,0]
	v_pk_mul_f32 v[38:39], v[38:39], v[2:3] op_sel_hi:[1,0]
	v_pk_mul_f32 v[36:37], v[36:37], v[2:3] op_sel_hi:[1,0]
	v_pk_mul_f32 v[34:35], v[34:35], v[2:3] op_sel_hi:[1,0]
	v_pk_mul_f32 v[32:33], v[32:33], v[2:3] op_sel_hi:[1,0]
	v_pk_mul_f32 v[30:31], v[30:31], v[2:3] op_sel_hi:[1,0]
	v_pk_mul_f32 v[28:29], v[28:29], v[2:3] op_sel_hi:[1,0]
	v_pk_mul_f32 v[26:27], v[26:27], v[2:3] op_sel_hi:[1,0]
	v_pk_mul_f32 v[24:25], v[24:25], v[2:3] op_sel_hi:[1,0]
	v_pk_mul_f32 v[22:23], v[22:23], v[2:3] op_sel_hi:[1,0]
	v_pk_mul_f32 v[20:21], v[20:21], v[2:3] op_sel_hi:[1,0]
	v_pk_mul_f32 v[18:19], v[18:19], v[2:3] op_sel_hi:[1,0]
	v_pk_mul_f32 v[16:17], v[16:17], v[2:3] op_sel_hi:[1,0]
	v_add_f32_e32 v3, v96, v97
	v_cvt_pk_bf16_f32 v96, v98, v0
	v_add3_u32 v0, s25, v141, v192
	v_add_u32_e32 v0, 0x4000, v0
	v_cvt_pk_bf16_f32 v97, v99, v10
	v_cvt_pk_bf16_f32 v99, v106, v6
	v_cvt_pk_bf16_f32 v80, v102, v80
	v_cvt_pk_bf16_f32 v81, v103, v82
	v_cvt_pk_bf16_f32 v82, v105, v84
	v_cvt_pk_bf16_f32 v83, v107, v86
	v_cvt_pk_bf16_f32 v6, v108, v12
	v_cvt_pk_bf16_f32 v9, v114, v100
	v_cvt_pk_bf16_f32 v10, v109, v88
	v_cvt_pk_bf16_f32 v11, v111, v90
	v_cvt_pk_bf16_f32 v12, v113, v92
	v_cvt_pk_bf16_f32 v13, v115, v94
	ds_read_b128 v[84:87], v0 offset:1024
	ds_read_b128 v[88:91], v0 offset:1056
	ds_read_b128 v[92:95], v0 offset:1088
	ds_read_b128 v[100:103], v0 offset:1120
	v_add3_u32 v0, s25, v192, v141
	v_cvt_pk_bf16_f32 v7, v110, v4
	v_add_u32_e32 v4, 0x5000, v0
	v_cvt_pk_bf16_f32 v98, v104, v14
	v_cvt_pk_bf16_f32 v8, v112, v8
	ds_read_b128 v[104:107], v4 offset:1536
	ds_read_b128 v[108:111], v4 offset:1568
	ds_read_b128 v[112:115], v4 offset:1600
	ds_read_b128 v[116:119], v4 offset:1632
	s_waitcnt lgkmcnt(7)
; template <int MODE> ...
;     ...
;             {
;                 bf16x8 vcur[4], vnxt[4];
;                 AT_LOADV(vcur, 0);
; #pragma unroll
;                 for (int dvb = 0; dvb < NDV; ++dvb) {
;                     if (dvb + 1 < NDV) AT_LOADV(vnxt, dvb + 1);
;                     __builtin_amdgcn_sched_barrier(0);
; #pragma unroll
;                     for (int i = 0; i < 4; ++i) acc[dvb] = __builtin_amdgcn_mfma_f32_32x32x16_bf16(vcur[i], pf[i >> 1][i & 1], acc[dvb], 0, 0, 0);
;                     __builtin_amdgcn_sched_barrier(0);
; #pragma unroll
;                     for (int i = 0; i < 4; ++i) vcur[i] = vnxt[i];
;                 }
;             }
	v_mfma_f32_32x32x16_bf16 v[64:79], v[84:87], v[96:99], v[64:79]
	s_waitcnt lgkmcnt(6)
	v_mfma_f32_32x32x16_bf16 v[64:79], v[88:91], v[6:9], v[64:79]
	s_waitcnt lgkmcnt(5)
	v_mfma_f32_32x32x16_bf16 v[64:79], v[92:95], v[80:83], v[64:79]
	s_waitcnt lgkmcnt(4)
	v_mfma_f32_32x32x16_bf16 v[64:79], v[100:103], v[10:13], v[64:79]
	v_add_u32_e32 v4, 0x6000, v0
	ds_read_b128 v[84:87], v4 offset:2048
	ds_read_b128 v[88:91], v4 offset:2080
	ds_read_b128 v[92:95], v4 offset:2112
	ds_read_b128 v[100:103], v4 offset:2144
	s_waitcnt lgkmcnt(7)
	v_mfma_f32_32x32x16_bf16 v[48:63], v[104:107], v[96:99], v[48:63]
	s_waitcnt lgkmcnt(6)
	v_mfma_f32_32x32x16_bf16 v[48:63], v[108:111], v[6:9], v[48:63]
	s_waitcnt lgkmcnt(5)
	v_mfma_f32_32x32x16_bf16 v[48:63], v[112:115], v[80:83], v[48:63]
	s_waitcnt lgkmcnt(4)
	v_mfma_f32_32x32x16_bf16 v[48:63], v[116:119], v[10:13], v[48:63]
	v_add_u32_e32 v0, 0x7000, v0
	ds_read_b128 v[104:107], v0 offset:2560
	ds_read_b128 v[108:111], v0 offset:2592
	ds_read_b128 v[112:115], v0 offset:2624
	ds_read_b128 v[116:119], v0 offset:2656
	s_waitcnt lgkmcnt(7)
	v_mfma_f32_32x32x16_bf16 v[32:47], v[84:87], v[96:99], v[32:47]
	s_waitcnt lgkmcnt(6)
	v_mfma_f32_32x32x16_bf16 v[32:47], v[88:91], v[6:9], v[32:47]
	s_waitcnt lgkmcnt(5)
	v_mfma_f32_32x32x16_bf16 v[32:47], v[92:95], v[80:83], v[32:47]
	s_waitcnt lgkmcnt(4)
	v_mfma_f32_32x32x16_bf16 v[32:47], v[100:103], v[10:13], v[32:47]
	s_waitcnt lgkmcnt(3)
	v_mfma_f32_32x32x16_bf16 v[16:31], v[104:107], v[96:99], v[16:31]
	s_waitcnt lgkmcnt(2)
	v_mfma_f32_32x32x16_bf16 v[16:31], v[108:111], v[6:9], v[16:31]
	s_waitcnt lgkmcnt(1)
	v_mfma_f32_32x32x16_bf16 v[16:31], v[112:115], v[80:83], v[16:31]
	s_waitcnt lgkmcnt(0)
	v_mfma_f32_32x32x16_bf16 v[16:31], v[116:119], v[10:13], v[16:31]
	v_fmac_f32_e32 v3, v139, v2
	v_mov_b32_e32 v139, v3

; #define LAS __attribute__((address_space(3)))
; #define GAS __attribute__((address_space(1)))
; template <int MODE> ...
;     ...
;     const int q_lo = 128 * jblk + 32 * wq;
;     const int qi = q_lo + r32;
;     const size_t qtok = tok0 + (size_t)qi * dil;
;     bf16x8 qf[4];
; #pragma unroll
;     for (int ds = 0; ds < 4; ++ds) qf[ds] = *(const GAS bf16x8*)(QK + qtok * 2048 + (2 * hp + mp) * 64 + 16 * ds + 8 * hi);
;     const int kt_hi = 2 * jblk + 1;
;     const int kt_lo = (MODE == 0) ? 0 : ((jblk > 0) ? 2 * jblk - 2 : 0);
;     const int kp_row0 = tid >> 4, kp_c = tid & 15;
;     const int vp_row0 = tid >> 3, vp_c = tid & 7;
;     const bf16* ksrc = QK + 1024 + 2 * hp * 64 + kp_c * 8;
;     const bf16* vsrc = Vt + (size_t)(2 * hp * 64 + vp_row0) * TOK + vcol0 + vp_c * 8;
;     u32x4 kr0, kr1, vr0, vr1;
;     {
;         const int kv0 = 64 * kt_lo;
;         kr0 = *(const GAS u32x4*)(ksrc + (tok0 + (size_t)(kv0 + kp_row0) * dil) * 2048);
;         kr1 = *(const GAS u32x4*)(ksrc + (tok0 + (size_t)(kv0 + kp_row0 + 32) * dil) * 2048);
;         vr0 = *(const GAS u32x4*)(vsrc + kv0);
;         vr1 = *(const GAS u32x4*)(vsrc + (size_t)64 * TOK + kv0);
;         LAS unsigned char* kb = lds; LAS unsigned char* vb = lds + AT_KBYTES;
;         *(LAS u32x4*)(kb + kp_row0 * AT_KROW + kp_c * 16) = kr0; *(LAS u32x4*)(kb + (kp_row0 + 32) * AT_KROW + kp_c * 16) = kr1;
;         { LAS unsigned char* p0 = vb + vp_row0 * AT_VROW + vp_c * 16; LAS unsigned char* p1 = vb + (vp_row0 + 64) * AT_VROW + vp_c * 16;
;           *(LAS u32x2*)p0 = (u32x2){vr0.x, vr0.y}; *(LAS u32x2*)(p0 + 8) = (u32x2){vr0.z, vr0.w}; *(LAS u32x2*)p1 = (u32x2){vr1.x, vr1.y}; *(LAS u32x2*)(p1 + 8) = (u32x2){vr1.z, vr1.w}; }
;     }
;     f32x16 acc[NDV];
; #pragma unroll
;     for (int i = 0; i < NDV; ++i)
; #pragma unroll
;         for (int r = 0; r < 16; ++r) acc[i][r] = 0.f;
;     float mrun = -1e30f, lsum = 0.f;
.LBB0_401:
	v_mov_b32_e32 v0, v206
	s_waitcnt lgkmcnt(0)
	s_barrier
	v_mov_b32_e32 v139, v1
	v_ashrrev_i32_e32 v22, 3, v0
	s_waitcnt vmcnt(0)
	v_add_u32_e32 v4, s18, v22
	v_ashrrev_i32_e32 v5, 31, v4
	v_lshlrev_b64 v[4:5], 17, v[4:5]
	v_ashrrev_i32_e32 v18, 4, v0
	v_lshlrev_b32_e32 v6, 4, v0
	v_lshl_add_u64 v[4:5], s[64:65], 0, v[4:5]
	v_lshl_add_u64 v[4:5], s[4:5], 1, v[4:5]
	v_and_b32_e32 v138, 0x70, v6
	v_ashrrev_i32_e32 v19, 31, v18
	v_and_b32_e32 v136, 0xf0, v6
	v_mov_b32_e32 v137, v1
	v_lshl_add_u64 v[14:15], v[4:5], 0, v[138:139]
	v_lshl_add_u64 v[4:5], s[4:5], 0, v[18:19]
	v_readfirstlane_b32 s14, v0
	v_lshl_add_u64 v[2:3], s[10:11], 0, v[136:137]
	v_lshlrev_b64 v[4:5], 12, v[4:5]
	s_bfe_u32 s10, s14, 0x20006
	v_lshl_add_u64 v[6:7], v[2:3], 0, v[4:5]
	v_add_u32_e32 v4, 32, v18
	s_lshl_b32 s21, s10, 5
	v_ashrrev_i32_e32 v5, 31, v4
	v_and_b32_e32 v192, 31, v0
	s_or_b32 s15, s21, s89
	v_lshl_add_u64 v[4:5], s[4:5], 0, v[4:5]
	s_ashr_i32 s11, s14, 8
	v_or_b32_e32 v195, s15, v192
	v_lshlrev_b64 v[4:5], 12, v[4:5]
	v_or_b32_e32 v134, s4, v195
	v_mov_b32_e32 v135, s5
	s_lshl_b32 s4, s11, 6
	v_lshl_add_u64 v[2:3], v[2:3], 0, v[4:5]
	v_lshlrev_b64 v[20:21], 12, v[134:135]
	s_add_i32 s4, s4, s18
	global_load_dwordx4 v[2:5], v[2:3], off
	s_nop 0
	global_load_dwordx4 v[6:9], v[6:7], off
	s_nop 0
	global_load_dwordx4 v[10:13], v[14:15], off
	v_bfe_u32 v193, v0, 5, 1
	v_lshl_add_u64 v[20:21], s[40:41], 0, v[20:21]
	s_ashr_i32 s5, s4, 31
	v_add_co_u32_e32 v14, vcc, s87, v14
	v_lshl_add_u64 v[20:21], s[4:5], 1, v[20:21]
	v_lshlrev_b32_e32 v140, 4, v193
	v_mov_b32_e32 v141, v1
	v_addc_co_u32_e32 v15, vcc, 0, v15, vcc
	v_lshl_add_u64 v[20:21], v[20:21], 0, v[140:141]
	global_load_dwordx4 v[14:17], v[14:15], off
	s_nop 0
	global_load_dwordx4 v[124:127], v[20:21], off
	global_load_dwordx4 v[120:123], v[20:21], off offset:32
	global_load_dwordx4 v[116:119], v[20:21], off offset:64
	global_load_dwordx4 v[112:115], v[20:21], off offset:96
	v_mul_lo_u32 v198, v18, s50
	v_mul_u32_u24_e32 v199, 0x90, v22
	v_and_b32_e32 v191, 63, v0
	v_add_u32_e32 v20, s80, v22
	v_add3_u32 v0, 0, v198, v136
	v_and_b32_e32 v229, 0x60, v138
	v_bfe_u32 v212, v138, 4, 1
	v_lshl_or_b32 v229, v212, 3, v229
	v_add3_u32 v22, 0, v199, v229
	v_lshlrev_b32_e32 v190, 2, v193
	s_lshl_b32 s5, s11, 13
	v_ashrrev_i32_e32 v21, 31, v20
	v_add_u32_e32 v23, 0x4400, v22
	v_add_u32_e32 v22, 0x6800, v22
	v_or_b32_e32 v24, s21, v192
	s_add_i32 s23, s89, s21
	s_add_i32 s22, s5, 0
	v_lshlrev_b64 v[20:21], 17, v[20:21]
	v_sub_u32_e32 v201, v24, v190
	v_add_u32_e32 v24, s23, v192
	s_add_i32 s5, s22, 0x11800
	v_lshl_add_u64 v[20:21], v[20:21], 0, s[8:9]
	s_add_i32 s22, s22, 0x11714
	v_lshl_add_u64 v[142:143], v[20:21], 0, v[138:139]
	s_mov_b32 s19, 0
	s_lshr_b32 s4, s14, 6
	v_lshlrev_b32_e32 v141, 4, v193
	v_mul_u32_u24_e32 v197, 0x110, v192
	v_mul_u32_u24_e32 v194, 0x90, v192
	v_add_u32_e32 v200, 0x2200, v198
	s_lshl_b32 s20, s11, 7
	s_or_b32 s21, s15, 31
	v_mov_b32_e32 v139, 0
	v_mov_b32_e32 v196, 0xf149f2ca
	s_waitcnt vmcnt(6)
	ds_write_b128 v0, v[6:9]
	ds_write_b128 v0, v[2:5] offset:8704
	s_waitcnt vmcnt(5)
	ds_write2_b64 v23, v[10:11], v[12:13] offset1:2
	s_waitcnt vmcnt(4)
	ds_write2_b64 v22, v[14:15], v[16:17] offset1:2
	v_lshlrev_b64 v[2:3], 12, v[18:19]
	v_lshl_add_u64 v[2:3], s[12:13], 0, v[2:3]
	v_sub_u32_e32 v0, v24, v190
	v_lshl_add_u64 v[2:3], v[2:3], 0, v[136:137]
	v_mov_b32_e32 v14, v1
	v_mov_b32_e32 v15, v1
	v_lshl_add_u32 v202, v0, 2, s22
	v_lshl_add_u64 v[144:145], v[2:3], 0, s[0:1]
	v_mov_b32_e32 v0, v1
	v_mov_b32_e32 v2, v1
	v_mov_b32_e32 v3, v1
	v_mov_b32_e32 v4, v1
	v_mov_b32_e32 v5, v1
	v_mov_b32_e32 v6, v1
	v_mov_b32_e32 v7, v1
	v_mov_b32_e32 v8, v1
	v_mov_b32_e32 v9, v1
	v_mov_b32_e32 v10, v1
	v_mov_b32_e32 v11, v1
	v_mov_b32_e32 v12, v1
	v_mov_b32_e32 v13, v1
	v_mov_b64_e32 v[30:31], v[14:15]
	v_mov_b64_e32 v[46:47], v[14:15]
	v_mov_b64_e32 v[62:63], v[14:15]
	v_mov_b64_e32 v[78:79], v[14:15]
	s_movk_i32 s0, 0xffc0
	v_mov_b64_e32 v[28:29], v[12:13]
	v_mov_b64_e32 v[26:27], v[10:11]
	v_mov_b64_e32 v[24:25], v[8:9]
	v_mov_b64_e32 v[22:23], v[6:7]
	v_mov_b64_e32 v[20:21], v[4:5]
	v_mov_b64_e32 v[18:19], v[2:3]
	v_mov_b64_e32 v[16:17], v[0:1]
	v_mov_b64_e32 v[44:45], v[12:13]
	v_mov_b64_e32 v[42:43], v[10:11]
	v_mov_b64_e32 v[40:41], v[8:9]
	v_mov_b64_e32 v[38:39], v[6:7]
	v_mov_b64_e32 v[36:37], v[4:5]
	v_mov_b64_e32 v[34:35], v[2:3]
	v_mov_b64_e32 v[32:33], v[0:1]
	v_mov_b64_e32 v[60:61], v[12:13]
	v_mov_b64_e32 v[58:59], v[10:11]
	v_mov_b64_e32 v[56:57], v[8:9]
	v_mov_b64_e32 v[54:55], v[6:7]
	v_mov_b64_e32 v[52:53], v[4:5]
	v_mov_b64_e32 v[50:51], v[2:3]
	v_mov_b64_e32 v[48:49], v[0:1]
	v_mov_b64_e32 v[76:77], v[12:13]
	v_mov_b64_e32 v[74:75], v[10:11]
	v_mov_b64_e32 v[72:73], v[8:9]
	v_mov_b64_e32 v[70:71], v[6:7]
	v_mov_b64_e32 v[68:69], v[4:5]
	v_mov_b64_e32 v[66:67], v[2:3]
	v_mov_b64_e32 v[64:65], v[0:1]
; template <int MODE> ...
;     ...
;     for (int kt = kt_lo; kt <= kt_hi; ++kt) {
;         const int bufsel = (kt - kt_lo) & 1;
;         __syncthreads();
;         const bool more = kt < kt_hi;
;         if (more) {
;             const int kv1 = 64 * (kt + 1);
;             kr0 = *(const GAS u32x4*)(ksrc + (tok0 + (size_t)(kv1 + kp_row0) * dil) * 2048);
;             kr1 = *(const GAS u32x4*)(ksrc + (tok0 + (size_t)(kv1 + kp_row0 + 32) * dil) * 2048);
;             vr0 = *(const GAS u32x4*)(vsrc + kv1);
;             vr1 = *(const GAS u32x4*)(vsrc + (size_t)64 * TOK + kv1);
;             asm volatile("" ::: "memory");
;         }
;         const int kv0 = 64 * kt;
;         bool skip = kv0 > q_lo + 31;
;         if (MODE == 1) skip = skip || (kv0 + 63 < q_lo - 128);
;         if (!skip) {
;             const LAS unsigned char* kb = lds + bufsel * AT_BUF; const LAS unsigned char* vb = kb + AT_KBYTES;
;             f32x16 s0, s1;
; #pragma unroll
;             for (int r = 0; r < 16; ++r) { s0[r] = 0.f; s1[r] = 0.f; }
;             {
;                 bf16x8 ka[4], kc[4];
; #pragma unroll
;                 for (int ds = 0; ds < 4; ++ds) {
;                     ka[ds] = *(const LAS bf16x8*)(kb + r32 * AT_KROW + mp * 128 + (16 * ds + 8 * hi) * 2);
;                     kc[ds] = *(const LAS bf16x8*)(kb + (32 + r32) * AT_KROW + mp * 128 + (16 * ds + 8 * hi) * 2);
;                 }
;                 __builtin_amdgcn_sched_barrier(0);
; #pragma unroll
;                 for (int ds = 0; ds < 4; ++ds) {
;                     s0 = __builtin_amdgcn_mfma_f32_32x32x16_bf16(ka[ds], qf[ds], s0, 0, 0, 0);
;                     s1 = __builtin_amdgcn_mfma_f32_32x32x16_bf16(kc[ds], qf[ds], s1, 0, 0, 0);
;                 }
;             }
;             const int relbase = qi - kv0 - 4 * hi;
;             constexpr int cmax = (MODE == 0) ? 2047 : 128;
;             float mx = -1e30f;
;             bool interior = (kv0 + 63 <= q_lo);
;             if (MODE == 1) interior = interior && (q_lo + 31 - kv0 <= 128);
;             if (interior) {
;                 const LAS float* p = biasL + mp * 2048 + (relbase - 59);
; #pragma unroll
;                 for (int r = 0; r < 16; ++r) {
;                     const int o = 59 - ((r & 3) + 8 * (r >> 2));
;                     s0[r] += p[o]; s1[r] += p[o - 32];
;                     mx = fmaxf(mx, fmaxf(s0[r], s1[r]));
;                 }
.LBB0_402:
	v_lshl_add_u64 v[2:3], s[54:55], 0, v[144:145]
	v_add_co_u32_e32 v4, vcc, s90, v2
	v_lshl_add_u64 v[10:11], s[54:55], 0, v[142:143]
	s_nop 0
	v_addc_co_u32_e32 v5, vcc, 0, v3, vcc
	v_add_co_u32_e32 v6, vcc, s91, v2
	s_waitcnt lgkmcnt(0)
	s_nop 0
	v_addc_co_u32_e32 v7, vcc, 0, v3, vcc
	v_add_co_u32_e32 v12, vcc, 0x20000000, v10
	s_barrier
	s_nop 0
	v_addc_co_u32_e32 v13, vcc, 0, v11, vcc
	v_add_co_u32_e32 v14, vcc, 0x20800000, v10
	global_load_dwordx4 v[2:5], v[4:5], off offset:2048
	s_nop 0
	global_load_dwordx4 v[6:9], v[6:7], off offset:2048
	v_addc_co_u32_e32 v15, vcc, 0, v11, vcc
	global_load_dwordx4 v[10:13], v[12:13], off offset:128
	s_nop 0
	global_load_dwordx4 v[128:131], v[14:15], off offset:128
	s_and_b32 s9, s19, 1
	s_add_i32 s8, s0, 64
	s_cmp_gt_u32 s8, s21
	s_cbranch_scc1 .LBB0_408
	s_mul_i32 s1, s9, 0x8c00
	s_add_i32 s12, s1, 0
	s_add_i32 s1, s20, s12
	v_add3_u32 v0, s1, v197, v140
	ds_read_b128 v[80:83], v0
	ds_read_b128 v[148:151], v0 offset:32
	ds_read_b128 v[84:87], v0 offset:8704
	ds_read_b128 v[152:155], v0 offset:8736
	ds_read_b128 v[156:159], v0 offset:64
	ds_read_b128 v[160:163], v0 offset:96
	ds_read_b128 v[164:167], v0 offset:8768
	ds_read_b128 v[168:171], v0 offset:8800
	ds_read2_b32 v[14:15], v202 offset0:58 offset1:59
	ds_read2_b32 v[218:219], v202 offset0:26 offset1:27
	ds_read2_b32 v[220:221], v202 offset0:56 offset1:57
	ds_read2_b32 v[222:223], v202 offset0:24 offset1:25
	ds_read2_b32 v[224:225], v202 offset0:50 offset1:51
	ds_read2_b32 v[174:175], v202 offset0:18 offset1:19
	ds_read2_b32 v[226:227], v202 offset0:48 offset1:49
	s_waitcnt lgkmcnt(14)
	s_waitcnt vmcnt(7)
	v_mfma_f32_32x32x16_bf16 v[96:111], v[80:83], v[124:127], 0
	s_add_i32 s13, s0, 0x7f
	s_mov_b64 s[0:1], -1
	s_cmp_gt_u32 s13, s15
	ds_read2_b32 v[172:173], v202 offset0:16 offset1:17
	s_waitcnt lgkmcnt(13)
	v_mfma_f32_32x32x16_bf16 v[80:95], v[84:87], v[124:127], 0
	s_waitcnt vmcnt(6)
	v_mfma_f32_32x32x16_bf16 v[96:111], v[148:151], v[120:123], v[96:111]
	ds_read2_b32 v[242:243], v202 offset0:42 offset1:43
	ds_read2_b32 v[182:183], v202 offset0:10 offset1:11
	s_waitcnt lgkmcnt(14)
	v_mfma_f32_32x32x16_bf16 v[80:95], v[152:155], v[120:123], v[80:95]
	ds_read2_b32 v[176:177], v202 offset0:40 offset1:41
	s_waitcnt lgkmcnt(14)
	s_waitcnt vmcnt(5)
	v_mfma_f32_32x32x16_bf16 v[96:111], v[156:159], v[116:119], v[96:111]
	ds_read2_b32 v[184:185], v202 offset0:8 offset1:9
	s_waitcnt lgkmcnt(13)
	v_mfma_f32_32x32x16_bf16 v[80:95], v[164:167], v[116:119], v[80:95]
	s_waitcnt vmcnt(4)
	v_mfma_f32_32x32x16_bf16 v[96:111], v[160:163], v[112:115], v[96:111]
	ds_read2_b32 v[180:181], v202 offset0:34 offset1:35
	ds_read2_b32 v[188:189], v202 offset0:2 offset1:3
	s_waitcnt lgkmcnt(14)
	v_mfma_f32_32x32x16_bf16 v[80:95], v[168:171], v[112:115], v[80:95]
	ds_read2_b32 v[178:179], v202 offset0:32 offset1:33
	s_nop 11
	s_cbranch_scc1 .LdaB_bias_masked
	s_waitcnt lgkmcnt(14)
	v_pk_add_f32 v[14:15], v[96:97], v[14:15] op_sel:[0,1] op_sel_hi:[1,0]
	ds_read2_b32 v[186:187], v202 offset0:0 offset1:1
	s_waitcnt lgkmcnt(14)
	v_pk_add_f32 v[166:167], v[80:81], v[218:219] op_sel:[0,1] op_sel_hi:[1,0]
	s_waitcnt lgkmcnt(13)
	v_pk_add_f32 v[148:149], v[98:99], v[220:221] op_sel:[0,1] op_sel_hi:[1,0]
	s_waitcnt lgkmcnt(12)
	v_pk_add_f32 v[168:169], v[82:83], v[222:223] op_sel:[0,1] op_sel_hi:[1,0]
	s_waitcnt lgkmcnt(11)
	v_pk_add_f32 v[152:153], v[100:101], v[224:225] op_sel:[0,1] op_sel_hi:[1,0]
	s_waitcnt lgkmcnt(10)
	v_pk_add_f32 v[174:175], v[84:85], v[174:175] op_sel:[0,1] op_sel_hi:[1,0]
	s_waitcnt lgkmcnt(9)
	v_pk_add_f32 v[150:151], v[102:103], v[226:227] op_sel:[0,1] op_sel_hi:[1,0]
	s_waitcnt lgkmcnt(8)
	v_pk_add_f32 v[172:173], v[86:87], v[172:173] op_sel:[0,1] op_sel_hi:[1,0]
	s_waitcnt lgkmcnt(7)
	v_pk_add_f32 v[170:171], v[104:105], v[242:243] op_sel:[0,1] op_sel_hi:[1,0]
	s_waitcnt lgkmcnt(6)
	v_pk_add_f32 v[182:183], v[88:89], v[182:183] op_sel:[0,1] op_sel_hi:[1,0]
	s_waitcnt lgkmcnt(5)
	v_pk_add_f32 v[176:177], v[106:107], v[176:177] op_sel:[0,1] op_sel_hi:[1,0]
	s_waitcnt lgkmcnt(4)
	v_pk_add_f32 v[184:185], v[90:91], v[184:185] op_sel:[0,1] op_sel_hi:[1,0]
	s_waitcnt lgkmcnt(3)
	v_pk_add_f32 v[180:181], v[108:109], v[180:181] op_sel:[0,1] op_sel_hi:[1,0]
	s_waitcnt lgkmcnt(2)
	v_pk_add_f32 v[188:189], v[92:93], v[188:189] op_sel:[0,1] op_sel_hi:[1,0]
	s_waitcnt lgkmcnt(1)
	v_pk_add_f32 v[178:179], v[110:111], v[178:179] op_sel:[0,1] op_sel_hi:[1,0]
	s_waitcnt lgkmcnt(0)
	v_pk_add_f32 v[186:187], v[94:95], v[186:187] op_sel:[0,1] op_sel_hi:[1,0]
	v_max_f32_e32 v80, v14, v166
	v_max_f32_e32 v81, v15, v167
	v_max3_f32 v82, v80, s84, v81
	v_max_f32_e32 v80, v148, v168
	v_max_f32_e32 v81, v149, v169
	v_max3_f32 v82, v82, v80, v81
	v_max_f32_e32 v80, v152, v174
	v_max_f32_e32 v81, v153, v175
	v_max3_f32 v82, v82, v80, v81
	v_max_f32_e32 v80, v150, v172
	v_max_f32_e32 v81, v151, v173
	v_max3_f32 v82, v82, v80, v81
	v_max_f32_e32 v80, v170, v182
	v_max_f32_e32 v81, v171, v183
	v_max3_f32 v82, v82, v80, v81
	v_max_f32_e32 v80, v176, v184
	v_max_f32_e32 v81, v177, v185
	v_max3_f32 v82, v82, v80, v81
	v_max_f32_e32 v80, v180, v188
	v_max_f32_e32 v81, v181, v189
	v_max3_f32 v82, v82, v80, v81
	v_max_f32_e32 v80, v178, v186
	v_max_f32_e32 v81, v179, v187
	v_max3_f32 v0, v82, v80, v81
	s_branch .LBB0_407

; __device__ __forceinline__ unsigned cvt_pk_bf16(float lo, float hi) { f32x2_t v = {lo, hi}; bf16x2_t b = __builtin_convertvector(v, bf16x2_t); return __builtin_bit_cast(unsigned, b); }
; __device__ __forceinline__ float fast_exp2(float x) { return __builtin_amdgcn_exp2f(x); }
; template <int MODE> ...
;     ...
;             const float mnew = fmaxf(mrun, mx);
;             const float alpha = fast_exp2(mrun - mnew);
;             mrun = mnew;
;             float ps = 0.f;
; #pragma unroll
;             for (int r = 0; r < 16; ++r) { s0[r] = fast_exp2(s0[r] - mnew); s1[r] = fast_exp2(s1[r] - mnew); ps += s0[r] + s1[r]; }
;             lsum = lsum * alpha + ps;
; #pragma unroll
;             for (int i = 0; i < NDV; ++i)
; #pragma unroll
;                 for (int r = 0; r < 16; ++r) acc[i][r] *= alpha;
;             bf16x8 pf[2][2];
; #pragma unroll
;             for (int t = 0; t < 2; ++t) {
;                 u32x4 w0, w1;
;                 w0.x = cvt_pk_bf16(s0[8 * t + 0], s0[8 * t + 1]); w0.y = cvt_pk_bf16(s0[8 * t + 2], s0[8 * t + 3]); w0.z = cvt_pk_bf16(s0[8 * t + 4], s0[8 * t + 5]); w0.w = cvt_pk_bf16(s0[8 * t + 6], s0[8 * t + 7]);
;                 w1.x = cvt_pk_bf16(s1[8 * t + 0], s1[8 * t + 1]); w1.y = cvt_pk_bf16(s1[8 * t + 2], s1[8 * t + 3]); w1.z = cvt_pk_bf16(s1[8 * t + 4], s1[8 * t + 5]); w1.w = cvt_pk_bf16(s1[8 * t + 6], s1[8 * t + 7]);
;                 pf[0][t] = __builtin_bit_cast(bf16x8, w0); pf[1][t] = __builtin_bit_cast(bf16x8, w1);
;             }
;     ...
;             {
;                 bf16x8 vcur[4], vnxt[4];
;                 AT_LOADV(vcur, 0);
.Lresc_keep_B:
	v_sub_f32_e32 v85, v152, v83
	v_exp_f32_e32 v152, v85
	v_sub_f32_e32 v85, v174, v83
	v_exp_f32_e32 v155, v85
	v_sub_f32_e32 v85, v153, v83
	v_exp_f32_e32 v88, v85
	v_sub_f32_e32 v85, v175, v83
	v_exp_f32_e32 v86, v85
	v_sub_f32_e32 v85, v150, v83
	v_exp_f32_e32 v150, v85
	v_sub_f32_e32 v85, v172, v83
	v_exp_f32_e32 v153, v85
	v_sub_f32_e32 v85, v151, v83
	v_exp_f32_e32 v92, v85
	v_sub_f32_e32 v85, v173, v83
	v_exp_f32_e32 v90, v85
	v_sub_f32_e32 v85, v170, v83
	v_exp_f32_e32 v151, v85
	v_sub_f32_e32 v85, v182, v83
	v_exp_f32_e32 v156, v85
	v_sub_f32_e32 v85, v171, v83
	v_exp_f32_e32 v96, v85
	v_sub_f32_e32 v85, v183, v83
	v_exp_f32_e32 v94, v85
	v_sub_f32_e32 v85, v176, v83
	v_exp_f32_e32 v157, v85
	v_sub_f32_e32 v85, v184, v83
	v_exp_f32_e32 v158, v85
	v_sub_f32_e32 v85, v177, v83
	v_sub_f32_e32 v0, v14, v83
	v_exp_f32_e32 v100, v85
	v_sub_f32_e32 v85, v185, v83
	v_exp_f32_e32 v110, v0
	v_sub_f32_e32 v0, v166, v83
	v_sub_f32_e32 v14, v167, v83
	v_exp_f32_e32 v98, v85
	v_sub_f32_e32 v85, v180, v83
	v_exp_f32_e32 v137, v0
	v_sub_f32_e32 v0, v15, v83
	v_exp_f32_e32 v80, v14
	v_sub_f32_e32 v14, v148, v83
	v_exp_f32_e32 v159, v85
	v_sub_f32_e32 v85, v188, v83
	v_exp_f32_e32 v0, v0
	v_exp_f32_e32 v111, v14
	v_sub_f32_e32 v14, v168, v83
	v_exp_f32_e32 v160, v85
	v_sub_f32_e32 v85, v181, v83
	v_exp_f32_e32 v154, v14
	v_sub_f32_e32 v14, v149, v83
	v_exp_f32_e32 v104, v85
	v_sub_f32_e32 v85, v189, v83
	v_exp_f32_e32 v84, v14
	v_sub_f32_e32 v14, v169, v83
	v_exp_f32_e32 v102, v85
	v_sub_f32_e32 v85, v178, v83
	v_add_f32_e32 v81, v137, v110
	v_exp_f32_e32 v14, v14
	v_exp_f32_e32 v161, v85
	v_sub_f32_e32 v85, v186, v83
	v_exp_f32_e32 v162, v85
	v_sub_f32_e32 v85, v179, v83
	v_pk_add_f32 v[108:109], v[80:81], v[0:1]
	v_exp_f32_e32 v148, v85
	v_sub_f32_e32 v85, v187, v83
	v_pk_add_f32 v[108:109], v[108:109], v[108:109] op_sel_hi:[0,1]
	v_add_f32_e32 v15, v154, v111
	v_exp_f32_e32 v106, v85
	v_mov_b32_e32 v85, v109
	v_pk_add_f32 v[108:109], v[14:15], v[84:85]
	v_add_f32_e32 v87, v155, v152
	v_pk_add_f32 v[108:109], v[108:109], v[108:109] op_sel_hi:[0,1]
	v_mov_b32_e32 v89, v109
	v_pk_add_f32 v[108:109], v[86:87], v[88:89]
	v_add_f32_e32 v91, v153, v150
	v_pk_add_f32 v[108:109], v[108:109], v[108:109] op_sel_hi:[0,1]
	v_mov_b32_e32 v93, v109
	v_pk_add_f32 v[108:109], v[90:91], v[92:93]
	v_add_f32_e32 v95, v156, v151
	v_pk_add_f32 v[108:109], v[108:109], v[108:109] op_sel_hi:[0,1]
	v_mov_b32_e32 v97, v109
	v_pk_add_f32 v[108:109], v[94:95], v[96:97]
	v_add_f32_e32 v99, v158, v157
	v_pk_add_f32 v[108:109], v[108:109], v[108:109] op_sel_hi:[0,1]
	v_mov_b32_e32 v101, v109
	v_pk_add_f32 v[108:109], v[98:99], v[100:101]
	v_add_f32_e32 v103, v160, v159
	v_pk_add_f32 v[108:109], v[108:109], v[108:109] op_sel_hi:[0,1]
	v_mov_b32_e32 v105, v109
	v_pk_add_f32 v[108:109], v[102:103], v[104:105]
	v_add_f32_e32 v107, v162, v161
	v_pk_add_f32 v[108:109], v[108:109], v[108:109] op_sel_hi:[0,1]
	v_mov_b32_e32 v149, v109
	v_pk_add_f32 v[108:109], v[106:107], v[148:149]
	v_cvt_pk_bf16_f32 v87, v153, v90
	v_add_f32_e32 v15, v108, v109
	v_cvt_pk_bf16_f32 v108, v110, v0
	v_add3_u32 v0, s12, v194, v141
	v_add_u32_e32 v0, 0x4000, v0
	v_cvt_pk_bf16_f32 v109, v111, v84
	v_cvt_pk_bf16_f32 v110, v152, v88
	v_cvt_pk_bf16_f32 v111, v150, v92
	v_cvt_pk_bf16_f32 v88, v151, v96
	v_cvt_pk_bf16_f32 v89, v157, v100
	v_cvt_pk_bf16_f32 v90, v159, v104
	v_cvt_pk_bf16_f32 v91, v161, v148
	v_cvt_pk_bf16_f32 v92, v156, v94
	v_cvt_pk_bf16_f32 v93, v158, v98
	v_cvt_pk_bf16_f32 v94, v160, v102
	v_cvt_pk_bf16_f32 v95, v162, v106
	ds_read_b128 v[96:99], v0 offset:1024
	ds_read_b128 v[100:103], v0 offset:1056
	ds_read_b128 v[104:107], v0 offset:1088
	ds_read_b128 v[148:151], v0 offset:1120
	v_add3_u32 v0, s12, v141, v194
	v_cvt_pk_bf16_f32 v85, v154, v14
	v_add_u32_e32 v14, 0x5000, v0
	v_cvt_pk_bf16_f32 v86, v155, v86
	ds_read_b128 v[152:155], v14 offset:1536
	ds_read_b128 v[156:159], v14 offset:1568
	ds_read_b128 v[160:163], v14 offset:1600
	ds_read_b128 v[164:167], v14 offset:1632
	v_sub_f32_e32 v82, v196, v83
	v_exp_f32_e32 v82, v82
	v_cvt_pk_bf16_f32 v84, v137, v80
	s_cmp_eq_u64 s[100:101], 0
	s_cbranch_scc1 .Lresc_skip_B
	v_pk_mul_f32 v[78:79], v[78:79], v[82:83] op_sel_hi:[1,0]
	v_pk_mul_f32 v[76:77], v[76:77], v[82:83] op_sel_hi:[1,0]
	v_pk_mul_f32 v[74:75], v[74:75], v[82:83] op_sel_hi:[1,0]
	v_pk_mul_f32 v[72:73], v[72:73], v[82:83] op_sel_hi:[1,0]
	v_pk_mul_f32 v[70:71], v[70:71], v[82:83] op_sel_hi:[1,0]
	v_pk_mul_f32 v[68:69], v[68:69], v[82:83] op_sel_hi:[1,0]
	v_pk_mul_f32 v[66:67], v[66:67], v[82:83] op_sel_hi:[1,0]
	v_pk_mul_f32 v[64:65], v[64:65], v[82:83] op_sel_hi:[1,0]
	v_pk_mul_f32 v[62:63], v[62:63], v[82:83] op_sel_hi:[1,0]
	v_pk_mul_f32 v[60:61], v[60:61], v[82:83] op_sel_hi:[1,0]
	v_pk_mul_f32 v[58:59], v[58:59], v[82:83] op_sel_hi:[1,0]
	v_pk_mul_f32 v[56:57], v[56:57], v[82:83] op_sel_hi:[1,0]
	v_pk_mul_f32 v[54:55], v[54:55], v[82:83] op_sel_hi:[1,0]
	v_pk_mul_f32 v[52:53], v[52:53], v[82:83] op_sel_hi:[1,0]
	v_pk_mul_f32 v[50:51], v[50:51], v[82:83] op_sel_hi:[1,0]
	v_pk_mul_f32 v[48:49], v[48:49], v[82:83] op_sel_hi:[1,0]
	v_pk_mul_f32 v[46:47], v[46:47], v[82:83] op_sel_hi:[1,0]
	v_pk_mul_f32 v[44:45], v[44:45], v[82:83] op_sel_hi:[1,0]
	v_pk_mul_f32 v[42:43], v[42:43], v[82:83] op_sel_hi:[1,0]
	v_pk_mul_f32 v[40:41], v[40:41], v[82:83] op_sel_hi:[1,0]
	v_pk_mul_f32 v[38:39], v[38:39], v[82:83] op_sel_hi:[1,0]
	v_pk_mul_f32 v[36:37], v[36:37], v[82:83] op_sel_hi:[1,0]
	v_pk_mul_f32 v[34:35], v[34:35], v[82:83] op_sel_hi:[1,0]
	v_pk_mul_f32 v[32:33], v[32:33], v[82:83] op_sel_hi:[1,0]
	v_pk_mul_f32 v[30:31], v[30:31], v[82:83] op_sel_hi:[1,0]
	v_pk_mul_f32 v[28:29], v[28:29], v[82:83] op_sel_hi:[1,0]
	v_pk_mul_f32 v[26:27], v[26:27], v[82:83] op_sel_hi:[1,0]
	v_pk_mul_f32 v[24:25], v[24:25], v[82:83] op_sel_hi:[1,0]
	v_pk_mul_f32 v[22:23], v[22:23], v[82:83] op_sel_hi:[1,0]
	v_pk_mul_f32 v[20:21], v[20:21], v[82:83] op_sel_hi:[1,0]
	v_pk_mul_f32 v[18:19], v[18:19], v[82:83] op_sel_hi:[1,0]
	v_pk_mul_f32 v[16:17], v[16:17], v[82:83] op_sel_hi:[1,0]
; #define LAS __attribute__((address_space(3)))
; template <int MODE> ...
;     ...
;             {
;                 bf16x8 vcur[4], vnxt[4];
;                 AT_LOADV(vcur, 0);
; #pragma unroll
;                 for (int dvb = 0; dvb < NDV; ++dvb) {
;                     if (dvb + 1 < NDV) AT_LOADV(vnxt, dvb + 1);
;                     __builtin_amdgcn_sched_barrier(0);
; #pragma unroll
;                     for (int i = 0; i < 4; ++i) acc[dvb] = __builtin_amdgcn_mfma_f32_32x32x16_bf16(vcur[i], pf[i >> 1][i & 1], acc[dvb], 0, 0, 0);
;                     __builtin_amdgcn_sched_barrier(0);
; #pragma unroll
;                     for (int i = 0; i < 4; ++i) vcur[i] = vnxt[i];
;                 }
;             }
;     ...
;         }
;         if (more) {
;             LAS unsigned char* kb = lds + (bufsel ^ 1) * AT_BUF; LAS unsigned char* vb = kb + AT_KBYTES;
;             *(LAS u32x4*)(kb + kp_row0 * AT_KROW + kp_c * 16) = kr0; *(LAS u32x4*)(kb + (kp_row0 + 32) * AT_KROW + kp_c * 16) = kr1;
;             { LAS unsigned char* p0 = vb + vp_row0 * AT_VROW + vp_c * 16; LAS unsigned char* p1 = vb + (vp_row0 + 64) * AT_VROW + vp_c * 16;
;           *(LAS u32x2*)p0 = (u32x2){vr0.x, vr0.y}; *(LAS u32x2*)(p0 + 8) = (u32x2){vr0.z, vr0.w}; *(LAS u32x2*)p1 = (u32x2){vr1.x, vr1.y}; *(LAS u32x2*)(p1 + 8) = (u32x2){vr1.z, vr1.w}; }
;         }
.Lresc_skip_B:
	s_waitcnt lgkmcnt(7)
	v_mfma_f32_32x32x16_bf16 v[64:79], v[96:99], v[108:111], v[64:79]
	s_waitcnt lgkmcnt(6)
	v_mfma_f32_32x32x16_bf16 v[64:79], v[100:103], v[88:91], v[64:79]
	s_waitcnt lgkmcnt(5)
	v_mfma_f32_32x32x16_bf16 v[64:79], v[104:107], v[84:87], v[64:79]
	s_waitcnt lgkmcnt(4)
	v_mfma_f32_32x32x16_bf16 v[64:79], v[148:151], v[92:95], v[64:79]
	v_add_u32_e32 v14, 0x6000, v0
	ds_read_b128 v[96:99], v14 offset:2048
	ds_read_b128 v[100:103], v14 offset:2080
	ds_read_b128 v[104:107], v14 offset:2112
	ds_read_b128 v[148:151], v14 offset:2144
	s_waitcnt lgkmcnt(7)
	v_mfma_f32_32x32x16_bf16 v[48:63], v[152:155], v[108:111], v[48:63]
	s_waitcnt lgkmcnt(6)
	v_mfma_f32_32x32x16_bf16 v[48:63], v[156:159], v[88:91], v[48:63]
	s_waitcnt lgkmcnt(5)
	v_mfma_f32_32x32x16_bf16 v[48:63], v[160:163], v[84:87], v[48:63]
	s_waitcnt lgkmcnt(4)
	v_mfma_f32_32x32x16_bf16 v[48:63], v[164:167], v[92:95], v[48:63]
	v_add_u32_e32 v0, 0x7000, v0
	ds_read_b128 v[152:155], v0 offset:2560
	ds_read_b128 v[156:159], v0 offset:2592
	ds_read_b128 v[160:163], v0 offset:2624
	ds_read_b128 v[164:167], v0 offset:2656
	s_waitcnt lgkmcnt(7)
	v_mfma_f32_32x32x16_bf16 v[32:47], v[96:99], v[108:111], v[32:47]
	s_waitcnt lgkmcnt(6)
	v_mfma_f32_32x32x16_bf16 v[32:47], v[100:103], v[88:91], v[32:47]
	s_waitcnt lgkmcnt(5)
	v_mfma_f32_32x32x16_bf16 v[32:47], v[104:107], v[84:87], v[32:47]
	s_waitcnt lgkmcnt(4)
	v_mfma_f32_32x32x16_bf16 v[32:47], v[148:151], v[92:95], v[32:47]
	s_waitcnt lgkmcnt(3)
	v_mfma_f32_32x32x16_bf16 v[16:31], v[152:155], v[108:111], v[16:31]
	s_waitcnt lgkmcnt(2)
	v_mfma_f32_32x32x16_bf16 v[16:31], v[156:159], v[88:91], v[16:31]
	s_waitcnt lgkmcnt(1)
	v_mfma_f32_32x32x16_bf16 v[16:31], v[160:163], v[84:87], v[16:31]
	s_waitcnt lgkmcnt(0)
	v_mfma_f32_32x32x16_bf16 v[16:31], v[164:167], v[92:95], v[16:31]
	v_fmac_f32_e32 v15, v139, v82
	v_mov_b32_e32 v196, v83
	v_mov_b32_e32 v139, v15
.LBB0_408:
	s_xor_b32 s0, s9, 1
	s_mul_i32 s0, s0, 0x8c00
	s_add_i32 s0, s0, 0
	v_add3_u32 v0, s0, v198, v136
	s_waitcnt vmcnt(3)
	ds_write_b128 v0, v[2:5]
	v_add3_u32 v0, s0, v200, v136
	s_waitcnt vmcnt(2)
	ds_write_b128 v0, v[6:9]
	v_add3_u32 v0, s0, v199, v229
	s_add_i32 s19, s19, 1
	v_add_u32_e32 v2, 0x4400, v0
	v_lshl_add_u64 v[142:143], v[142:143], 0, s[96:97]
	v_subrev_u32_e32 v201, 64, v201
	v_add_u32_e32 v202, 0xffffff00, v202
	s_cmp_eq_u32 s89, s8
	v_lshl_add_u64 v[144:145], v[144:145], 0, s[94:95]
	v_add_u32_e32 v0, 0x6800, v0
	s_waitcnt vmcnt(1)
	ds_write2_b64 v2, v[10:11], v[12:13] offset1:2
	s_waitcnt vmcnt(0)
	ds_write2_b64 v0, v[128:129], v[130:131] offset1:2
	s_cbranch_scc1 .LBB0_410
	s_mov_b32 s0, s8
	s_branch .LBB0_402
; #define LAS __attribute__((address_space(3)))
; template <int MODE> ...
;     ...
;         const int kv0 = 64 * kt;
;         bool skip = kv0 > q_lo + 31;
;         if (MODE == 1) skip = skip || (kv0 + 63 < q_lo - 128);
;         if (!skip) {
;             const LAS unsigned char* kb = lds + bufsel * AT_BUF; const LAS unsigned char* vb = kb + AT_KBYTES;
;             f32x16 s0, s1;
; #pragma unroll
;             for (int r = 0; r < 16; ++r) { s0[r] = 0.f; s1[r] = 0.f; }
;             {
;                 bf16x8 ka[4], kc[4];
; #pragma unroll
;                 for (int ds = 0; ds < 4; ++ds) {
;                     ka[ds] = *(const LAS bf16x8*)(kb + r32 * AT_KROW + mp * 128 + (16 * ds + 8 * hi) * 2);
;                     kc[ds] = *(const LAS bf16x8*)(kb + (32 + r32) * AT_KROW + mp * 128 + (16 * ds + 8 * hi) * 2);
;                 }
;                 __builtin_amdgcn_sched_barrier(0);
; #pragma unroll
;                 for (int ds = 0; ds < 4; ++ds) {
;                     s0 = __builtin_amdgcn_mfma_f32_32x32x16_bf16(ka[ds], qf[ds], s0, 0, 0, 0);
;                     s1 = __builtin_amdgcn_mfma_f32_32x32x16_bf16(kc[ds], qf[ds], s1, 0, 0, 0);
;                 }
;             }
;             const int relbase = qi - kv0 - 4 * hi;
;             constexpr int cmax = (MODE == 0) ? 2047 : 128;
;             float mx = -1e30f;
;             bool interior = (kv0 + 63 <= q_lo);
;             if (MODE == 1) interior = interior && (q_lo + 31 - kv0 <= 128);
;             if (interior) {
;                 const LAS float* p = biasL + mp * 2048 + (relbase - 59);
; #pragma unroll
;                 for (int r = 0; r < 16; ++r) {
;                     const int o = 59 - ((r & 3) + 8 * (r >> 2));
;                     s0[r] += p[o]; s1[r] += p[o - 32];
;                     mx = fmaxf(mx, fmaxf(s0[r], s1[r]));
;                 }
.LBB0_410:
	s_lshl_b32 s0, s19, 6
	s_cmp_gt_u32 s0, s21
	s_waitcnt lgkmcnt(0)
	s_barrier
	s_cbranch_scc1 .LBB0_416
	s_bitcmp1_b32 s19, 0
	s_cselect_b32 s1, 0x8c00, 0
	s_add_i32 s8, s1, 0
	s_add_i32 s20, s20, s8
	v_add3_u32 v0, s20, v197, v140
	ds_read_b128 v[2:5], v0
	ds_read_b128 v[6:9], v0 offset:32
	ds_read_b128 v[10:13], v0 offset:8704
	ds_read_b128 v[128:131], v0 offset:8736
	ds_read_b128 v[142:145], v0 offset:64
	ds_read_b128 v[148:151], v0 offset:96
	ds_read_b128 v[152:155], v0 offset:8768
	ds_read_b128 v[156:159], v0 offset:8800
	s_waitcnt lgkmcnt(7)
	v_mfma_f32_32x32x16_bf16 v[96:111], v[2:5], v[124:127], 0
	v_or_b32_e32 v0, s0, v190
	s_or_b32 s9, s0, 63
	v_sub_u32_e32 v0, v195, v0
	s_mov_b64 s[0:1], -1
	s_cmp_gt_u32 s9, s15
	s_waitcnt lgkmcnt(5)
	v_mfma_f32_32x32x16_bf16 v[80:95], v[10:13], v[124:127], 0
	v_mfma_f32_32x32x16_bf16 v[96:111], v[6:9], v[120:123], v[96:111]
	s_waitcnt lgkmcnt(4)
	v_mfma_f32_32x32x16_bf16 v[80:95], v[128:131], v[120:123], v[80:95]
	s_waitcnt lgkmcnt(3)
	v_mfma_f32_32x32x16_bf16 v[96:111], v[142:145], v[116:119], v[96:111]
	s_waitcnt lgkmcnt(1)
	v_mfma_f32_32x32x16_bf16 v[80:95], v[152:155], v[116:119], v[80:95]
	v_mfma_f32_32x32x16_bf16 v[96:111], v[148:151], v[112:115], v[96:111]
	s_waitcnt lgkmcnt(0)
	v_mfma_f32_32x32x16_bf16 v[80:95], v[156:159], v[112:115], v[80:95]
	s_cbranch_scc1 .LBB0_413
	v_lshl_add_u32 v118, v0, 2, s5
	v_add_u32_e32 v2, -4, v118
	v_add_u32_e32 v4, 0xffffff7c, v118
	ds_read2_b32 v[2:3], v2 offset1:1
	ds_read2_b32 v[4:5], v4 offset1:1
	v_add_u32_e32 v6, -12, v118
	v_add_u32_e32 v8, 0xffffff14, v118
	ds_read2_b32 v[6:7], v6 offset1:1
	ds_read2_b32 v[112:113], v8 offset1:1
	s_waitcnt lgkmcnt(3)
	v_pk_add_f32 v[116:117], v[96:97], v[2:3] op_sel:[0,1] op_sel_hi:[1,0]
	s_waitcnt lgkmcnt(2)
	v_pk_add_f32 v[128:129], v[80:81], v[4:5] op_sel:[0,1] op_sel_hi:[1,0]
	v_subrev_u32_e32 v4, 36, v118
	v_max_f32_e32 v2, v116, v128
	v_max_f32_e32 v3, v117, v129
	v_max3_f32 v12, v2, s84, v3
	v_add_u32_e32 v2, 0xffffff74, v118
	ds_read2_b32 v[2:3], v2 offset1:1
	s_waitcnt lgkmcnt(2)
	v_pk_add_f32 v[10:11], v[98:99], v[6:7] op_sel:[0,1] op_sel_hi:[1,0]
	v_add_u32_e32 v6, 0xffffff5c, v118
	v_subrev_u32_e32 v8, 44, v118
	ds_read2_b32 v[4:5], v4 offset1:1
	ds_read2_b32 v[6:7], v6 offset1:1
	ds_read2_b32 v[8:9], v8 offset1:1
	s_waitcnt lgkmcnt(3)
	v_pk_add_f32 v[136:137], v[82:83], v[2:3] op_sel:[0,1] op_sel_hi:[1,0]
	v_add_u32_e32 v13, 0xffffffb4, v118
	v_max_f32_e32 v2, v10, v136
	v_max_f32_e32 v3, v11, v137
	s_waitcnt lgkmcnt(2)
	v_pk_add_f32 v[14:15], v[100:101], v[4:5] op_sel:[0,1] op_sel_hi:[1,0]
	s_waitcnt lgkmcnt(1)
	v_pk_add_f32 v[124:125], v[84:85], v[6:7] op_sel:[0,1] op_sel_hi:[1,0]
	v_max3_f32 v2, v12, v2, v3
	v_max_f32_e32 v3, v14, v124
	v_max_f32_e32 v4, v15, v125
	v_max3_f32 v12, v2, v3, v4
	v_add_u32_e32 v2, 0xffffff54, v118
	ds_read2_b32 v[2:3], v2 offset1:1
	s_waitcnt lgkmcnt(1)
	v_pk_add_f32 v[6:7], v[102:103], v[8:9] op_sel:[0,1] op_sel_hi:[1,0]
	v_add_u32_e32 v4, 0xffffffbc, v118
	v_add_u32_e32 v8, 0xffffff3c, v118
	ds_read2_b32 v[4:5], v4 offset1:1
	ds_read2_b32 v[8:9], v8 offset1:1
	ds_read2_b32 v[114:115], v13 offset1:1
	s_waitcnt lgkmcnt(3)
	v_pk_add_f32 v[130:131], v[86:87], v[2:3] op_sel:[0,1] op_sel_hi:[1,0]
	s_mov_b64 s[0:1], 0
	v_max_f32_e32 v2, v6, v130
	v_max_f32_e32 v3, v7, v131
	v_max3_f32 v2, v12, v2, v3
	s_waitcnt lgkmcnt(2)
	v_pk_add_f32 v[12:13], v[104:105], v[4:5] op_sel:[0,1] op_sel_hi:[1,0]
	s_waitcnt lgkmcnt(1)
	v_pk_add_f32 v[122:123], v[88:89], v[8:9] op_sel:[0,1] op_sel_hi:[1,0]
	v_add_u32_e32 v8, 0xffffff9c, v118
	v_max_f32_e32 v3, v12, v122
	v_max_f32_e32 v4, v13, v123
	v_max3_f32 v120, v2, v3, v4
	v_add_u32_e32 v2, 0xffffff34, v118
	ds_read2_b32 v[2:3], v2 offset1:1
	s_waitcnt lgkmcnt(1)
	v_pk_add_f32 v[4:5], v[106:107], v[114:115] op_sel:[0,1] op_sel_hi:[1,0]
	v_add_u32_e32 v114, 0xffffff1c, v118
	v_add_u32_e32 v118, 0xffffff94, v118
	ds_read2_b32 v[8:9], v8 offset1:1
	ds_read2_b32 v[114:115], v114 offset1:1
	ds_read2_b32 v[118:119], v118 offset1:1
	s_waitcnt lgkmcnt(3)
	v_pk_add_f32 v[126:127], v[90:91], v[2:3] op_sel:[0,1] op_sel_hi:[1,0]
	s_waitcnt lgkmcnt(2)
	v_pk_add_f32 v[8:9], v[108:109], v[8:9] op_sel:[0,1] op_sel_hi:[1,0]
	v_max_f32_e32 v2, v4, v126
	v_max_f32_e32 v3, v5, v127
	v_max3_f32 v2, v120, v2, v3
	s_waitcnt lgkmcnt(1)
	v_pk_add_f32 v[120:121], v[92:93], v[114:115] op_sel:[0,1] op_sel_hi:[1,0]
	s_nop 0
	v_max_f32_e32 v3, v8, v120
	v_max_f32_e32 v114, v9, v121
	v_max3_f32 v114, v2, v3, v114
	s_waitcnt lgkmcnt(0)
	v_pk_add_f32 v[2:3], v[110:111], v[118:119] op_sel:[0,1] op_sel_hi:[1,0]
	v_pk_add_f32 v[118:119], v[94:95], v[112:113] op_sel:[0,1] op_sel_hi:[1,0]
	s_nop 0
	v_max_f32_e32 v112, v2, v118
	v_max_f32_e32 v113, v3, v119
	v_max3_f32 v138, v114, v112, v113

; __device__ __forceinline__ unsigned cvt_pk_bf16(float lo, float hi) { f32x2_t v = {lo, hi}; bf16x2_t b = __builtin_convertvector(v, bf16x2_t); return __builtin_bit_cast(unsigned, b); }
; __device__ __forceinline__ float max_x32(float v) { auto rr = __builtin_amdgcn_permlane32_swap(__float_as_uint(v), __float_as_uint(v), false, false); return fmaxf(__uint_as_float(rr[0]), __uint_as_float(rr[1])); }
; __device__ __forceinline__ float fast_exp2(float x) { return __builtin_amdgcn_exp2f(x); }
; template <int MODE> ...
;     ...
;             mx = max_x32(mx);
;             const float mnew = fmaxf(mrun, mx);
;             const float alpha = fast_exp2(mrun - mnew);
;             mrun = mnew;
;             float ps = 0.f;
; #pragma unroll
;             for (int r = 0; r < 16; ++r) { s0[r] = fast_exp2(s0[r] - mnew); s1[r] = fast_exp2(s1[r] - mnew); ps += s0[r] + s1[r]; }
;             lsum = lsum * alpha + ps;
; #pragma unroll
;             for (int i = 0; i < NDV; ++i)
; #pragma unroll
;                 for (int r = 0; r < 16; ++r) acc[i][r] *= alpha;
;             bf16x8 pf[2][2];
; #pragma unroll
;             for (int t = 0; t < 2; ++t) {
;                 u32x4 w0, w1;
;                 w0.x = cvt_pk_bf16(s0[8 * t + 0], s0[8 * t + 1]); w0.y = cvt_pk_bf16(s0[8 * t + 2], s0[8 * t + 3]); w0.z = cvt_pk_bf16(s0[8 * t + 4], s0[8 * t + 5]); w0.w = cvt_pk_bf16(s0[8 * t + 6], s0[8 * t + 7]);
;                 w1.x = cvt_pk_bf16(s1[8 * t + 0], s1[8 * t + 1]); w1.y = cvt_pk_bf16(s1[8 * t + 2], s1[8 * t + 3]); w1.z = cvt_pk_bf16(s1[8 * t + 4], s1[8 * t + 5]); w1.w = cvt_pk_bf16(s1[8 * t + 6], s1[8 * t + 7]);
;                 pf[0][t] = __builtin_bit_cast(bf16x8, w0); pf[1][t] = __builtin_bit_cast(bf16x8, w1);
;             }
;     ...
;             {
;                 bf16x8 vcur[4], vnxt[4];
;                 AT_LOADV(vcur, 0);
.LBB0_415:
	v_mov_b32_e32 v0, v138
	s_nop 1
	v_permlane32_swap_b32_e32 v138, v0
	s_nop 4
	v_max3_f32 v94, v196, v138, v0
	v_sub_f32_e32 v0, v116, v94
	v_exp_f32_e32 v98, v0
	v_sub_f32_e32 v0, v128, v94
	v_sub_f32_e32 v10, v10, v94
	v_sub_f32_e32 v6, v6, v94
	v_sub_f32_e32 v4, v4, v94
	v_exp_f32_e32 v102, v0
	v_sub_f32_e32 v0, v117, v94
	v_sub_f32_e32 v80, v129, v94
	v_exp_f32_e32 v99, v10
	v_sub_f32_e32 v10, v136, v94
	v_exp_f32_e32 v106, v6
	v_sub_f32_e32 v6, v130, v94
	v_exp_f32_e32 v110, v4
	v_sub_f32_e32 v4, v126, v94
	v_exp_f32_e32 v0, v0
	v_exp_f32_e32 v80, v80
	v_exp_f32_e32 v103, v10
	v_sub_f32_e32 v10, v11, v94
	v_sub_f32_e32 v11, v137, v94
	v_exp_f32_e32 v107, v6
	v_sub_f32_e32 v6, v7, v94
	v_sub_f32_e32 v7, v131, v94
	v_exp_f32_e32 v111, v4
	v_sub_f32_e32 v4, v5, v94
	v_sub_f32_e32 v5, v127, v94
	v_sub_f32_e32 v2, v2, v94
	v_exp_f32_e32 v82, v11
	v_sub_f32_e32 v11, v14, v94
	v_exp_f32_e32 v86, v7
	v_sub_f32_e32 v7, v12, v94
	v_exp_f32_e32 v90, v5
	v_sub_f32_e32 v5, v8, v94
	v_exp_f32_e32 v114, v2
	v_sub_f32_e32 v2, v118, v94
	v_exp_f32_e32 v104, v11
	v_sub_f32_e32 v11, v124, v94
	v_exp_f32_e32 v108, v7
	v_sub_f32_e32 v7, v122, v94
	v_exp_f32_e32 v112, v5
	v_sub_f32_e32 v5, v120, v94
	v_exp_f32_e32 v115, v2
	v_sub_f32_e32 v2, v3, v94
	v_sub_f32_e32 v96, v196, v94
	v_add_f32_e32 v81, v102, v98
	v_exp_f32_e32 v10, v10
	v_exp_f32_e32 v105, v11
	v_sub_f32_e32 v11, v15, v94
	v_exp_f32_e32 v109, v7
	v_sub_f32_e32 v7, v13, v94
	v_exp_f32_e32 v113, v5
	v_sub_f32_e32 v5, v9, v94
	v_exp_f32_e32 v100, v2
	v_sub_f32_e32 v2, v119, v94
	v_exp_f32_e32 v14, v11
	v_sub_f32_e32 v11, v125, v94
	v_exp_f32_e32 v12, v7
	v_sub_f32_e32 v7, v123, v94
	v_exp_f32_e32 v8, v5
	v_sub_f32_e32 v5, v121, v94
	v_exp_f32_e32 v94, v2
	v_exp_f32_e32 v2, v96
	v_pk_add_f32 v[96:97], v[80:81], v[0:1]
	v_add_f32_e32 v83, v103, v99
	v_pk_add_f32 v[96:97], v[96:97], v[96:97] op_sel_hi:[0,1]
	v_exp_f32_e32 v84, v11
	v_mov_b32_e32 v11, v97
	v_pk_add_f32 v[96:97], v[82:83], v[10:11]
	v_add_f32_e32 v85, v105, v104
	v_pk_add_f32 v[96:97], v[96:97], v[96:97] op_sel_hi:[0,1]
	v_exp_f32_e32 v6, v6
	v_mov_b32_e32 v15, v97
	v_pk_add_f32 v[96:97], v[84:85], v[14:15]
	v_add_f32_e32 v87, v107, v106
	v_pk_add_f32 v[96:97], v[96:97], v[96:97] op_sel_hi:[0,1]
	v_exp_f32_e32 v88, v7
	v_mov_b32_e32 v7, v97
	v_pk_add_f32 v[96:97], v[86:87], v[6:7]
	v_add_f32_e32 v89, v109, v108
	v_pk_add_f32 v[96:97], v[96:97], v[96:97] op_sel_hi:[0,1]
	v_exp_f32_e32 v4, v4
	v_mov_b32_e32 v13, v97
	v_pk_add_f32 v[96:97], v[88:89], v[12:13]
	v_add_f32_e32 v91, v111, v110
	v_pk_add_f32 v[96:97], v[96:97], v[96:97] op_sel_hi:[0,1]
	v_exp_f32_e32 v92, v5
	v_mov_b32_e32 v5, v97
	v_pk_add_f32 v[96:97], v[90:91], v[4:5]
	v_add_f32_e32 v93, v113, v112
	v_pk_add_f32 v[96:97], v[96:97], v[96:97] op_sel_hi:[0,1]
	v_mov_b32_e32 v9, v97
	v_pk_add_f32 v[96:97], v[92:93], v[8:9]
	v_add_f32_e32 v95, v115, v114
	v_pk_add_f32 v[96:97], v[96:97], v[96:97] op_sel_hi:[0,1]
	v_mov_b32_e32 v101, v97
	v_pk_add_f32 v[96:97], v[94:95], v[100:101]
	v_pk_mul_f32 v[78:79], v[78:79], v[2:3] op_sel_hi:[1,0]
	v_pk_mul_f32 v[76:77], v[76:77], v[2:3] op_sel_hi:[1,0]
	v_pk_mul_f32 v[74:75], v[74:75], v[2:3] op_sel_hi:[1,0]
	v_pk_mul_f32 v[72:73], v[72:73], v[2:3] op_sel_hi:[1,0]
	v_pk_mul_f32 v[70:71], v[70:71], v[2:3] op_sel_hi:[1,0]
	v_pk_mul_f32 v[68:69], v[68:69], v[2:3] op_sel_hi:[1,0]
	v_pk_mul_f32 v[66:67], v[66:67], v[2:3] op_sel_hi:[1,0]
	v_pk_mul_f32 v[64:65], v[64:65], v[2:3] op_sel_hi:[1,0]
	v_pk_mul_f32 v[62:63], v[62:63], v[2:3] op_sel_hi:[1,0]
	v_pk_mul_f32 v[60:61], v[60:61], v[2:3] op_sel_hi:[1,0]
	v_pk_mul_f32 v[58:59], v[58:59], v[2:3] op_sel_hi:[1,0]
	v_pk_mul_f32 v[56:57], v[56:57], v[2:3] op_sel_hi:[1,0]
	v_pk_mul_f32 v[54:55], v[54:55], v[2:3] op_sel_hi:[1,0]
	v_pk_mul_f32 v[52:53], v[52:53], v[2:3] op_sel_hi:[1,0]
	v_pk_mul_f32 v[50:51], v[50:51], v[2:3] op_sel_hi:[1,0]
	v_pk_mul_f32 v[48:49], v[48:49], v[2:3] op_sel_hi:[1,0]
	v_pk_mul_f32 v[46:47], v[46:47], v[2:3] op_sel_hi:[1,0]
	v_pk_mul_f32 v[44:45], v[44:45], v[2:3] op_sel_hi:[1,0]
	v_pk_mul_f32 v[42:43], v[42:43], v[2:3] op_sel_hi:[1,0]
	v_pk_mul_f32 v[40:41], v[40:41], v[2:3] op_sel_hi:[1,0]
	v_pk_mul_f32 v[38:39], v[38:39], v[2:3] op_sel_hi:[1,0]
	v_pk_mul_f32 v[36:37], v[36:37], v[2:3] op_sel_hi:[1,0]
	v_pk_mul_f32 v[34:35], v[34:35], v[2:3] op_sel_hi:[1,0]
	v_pk_mul_f32 v[32:33], v[32:33], v[2:3] op_sel_hi:[1,0]
	v_pk_mul_f32 v[30:31], v[30:31], v[2:3] op_sel_hi:[1,0]
	v_pk_mul_f32 v[28:29], v[28:29], v[2:3] op_sel_hi:[1,0]
	v_pk_mul_f32 v[26:27], v[26:27], v[2:3] op_sel_hi:[1,0]
	v_pk_mul_f32 v[24:25], v[24:25], v[2:3] op_sel_hi:[1,0]
	v_pk_mul_f32 v[22:23], v[22:23], v[2:3] op_sel_hi:[1,0]
	v_pk_mul_f32 v[20:21], v[20:21], v[2:3] op_sel_hi:[1,0]
	v_pk_mul_f32 v[18:19], v[18:19], v[2:3] op_sel_hi:[1,0]
	v_pk_mul_f32 v[16:17], v[16:17], v[2:3] op_sel_hi:[1,0]
	v_add_f32_e32 v3, v96, v97
	v_cvt_pk_bf16_f32 v96, v98, v0
	v_add3_u32 v0, s8, v194, v141
	v_add_u32_e32 v0, 0x4000, v0
	v_cvt_pk_bf16_f32 v97, v99, v10
	v_cvt_pk_bf16_f32 v99, v106, v6
	v_cvt_pk_bf16_f32 v80, v102, v80
	v_cvt_pk_bf16_f32 v81, v103, v82
	v_cvt_pk_bf16_f32 v82, v105, v84
	v_cvt_pk_bf16_f32 v83, v107, v86
	v_cvt_pk_bf16_f32 v6, v108, v12
	v_cvt_pk_bf16_f32 v9, v114, v100
	v_cvt_pk_bf16_f32 v10, v109, v88
	v_cvt_pk_bf16_f32 v11, v111, v90
	v_cvt_pk_bf16_f32 v12, v113, v92
	v_cvt_pk_bf16_f32 v13, v115, v94
	ds_read_b128 v[84:87], v0 offset:1024
	ds_read_b128 v[88:91], v0 offset:1056
	ds_read_b128 v[92:95], v0 offset:1088
	ds_read_b128 v[100:103], v0 offset:1120
	v_add3_u32 v0, s8, v141, v194
	v_cvt_pk_bf16_f32 v7, v110, v4
	v_add_u32_e32 v4, 0x5000, v0
	v_cvt_pk_bf16_f32 v98, v104, v14
	v_cvt_pk_bf16_f32 v8, v112, v8
	ds_read_b128 v[104:107], v4 offset:1536
	ds_read_b128 v[108:111], v4 offset:1568
	ds_read_b128 v[112:115], v4 offset:1600
	ds_read_b128 v[116:119], v4 offset:1632
	s_waitcnt lgkmcnt(7)
; template <int MODE> ...
;     ...
;             {
;                 bf16x8 vcur[4], vnxt[4];
;                 AT_LOADV(vcur, 0);
; #pragma unroll
;                 for (int dvb = 0; dvb < NDV; ++dvb) {
;                     if (dvb + 1 < NDV) AT_LOADV(vnxt, dvb + 1);
;                     __builtin_amdgcn_sched_barrier(0);
; #pragma unroll
;                     for (int i = 0; i < 4; ++i) acc[dvb] = __builtin_amdgcn_mfma_f32_32x32x16_bf16(vcur[i], pf[i >> 1][i & 1], acc[dvb], 0, 0, 0);
;                     __builtin_amdgcn_sched_barrier(0);
; #pragma unroll
;                     for (int i = 0; i < 4; ++i) vcur[i] = vnxt[i];
;                 }
;             }
	v_mfma_f32_32x32x16_bf16 v[64:79], v[84:87], v[96:99], v[64:79]
	s_waitcnt lgkmcnt(6)
	v_mfma_f32_32x32x16_bf16 v[64:79], v[88:91], v[6:9], v[64:79]
	s_waitcnt lgkmcnt(5)
	v_mfma_f32_32x32x16_bf16 v[64:79], v[92:95], v[80:83], v[64:79]
	s_waitcnt lgkmcnt(4)
	v_mfma_f32_32x32x16_bf16 v[64:79], v[100:103], v[10:13], v[64:79]
	v_add_u32_e32 v4, 0x6000, v0
	ds_read_b128 v[84:87], v4 offset:2048
	ds_read_b128 v[88:91], v4 offset:2080
	ds_read_b128 v[92:95], v4 offset:2112
	ds_read_b128 v[100:103], v4 offset:2144
	s_waitcnt lgkmcnt(7)
	v_mfma_f32_32x32x16_bf16 v[48:63], v[104:107], v[96:99], v[48:63]
	s_waitcnt lgkmcnt(6)
	v_mfma_f32_32x32x16_bf16 v[48:63], v[108:111], v[6:9], v[48:63]
	s_waitcnt lgkmcnt(5)
	v_mfma_f32_32x32x16_bf16 v[48:63], v[112:115], v[80:83], v[48:63]
	s_waitcnt lgkmcnt(4)
	v_mfma_f32_32x32x16_bf16 v[48:63], v[116:119], v[10:13], v[48:63]
	v_add_u32_e32 v0, 0x7000, v0
	ds_read_b128 v[104:107], v0 offset:2560
	ds_read_b128 v[108:111], v0 offset:2592
	ds_read_b128 v[112:115], v0 offset:2624
	ds_read_b128 v[116:119], v0 offset:2656
	s_waitcnt lgkmcnt(7)
	v_mfma_f32_32x32x16_bf16 v[32:47], v[84:87], v[96:99], v[32:47]
	s_waitcnt lgkmcnt(6)
	v_mfma_f32_32x32x16_bf16 v[32:47], v[88:91], v[6:9], v[32:47]
	s_waitcnt lgkmcnt(5)
	v_mfma_f32_32x32x16_bf16 v[32:47], v[92:95], v[80:83], v[32:47]
	s_waitcnt lgkmcnt(4)
	v_mfma_f32_32x32x16_bf16 v[32:47], v[100:103], v[10:13], v[32:47]
	s_waitcnt lgkmcnt(3)
	v_mfma_f32_32x32x16_bf16 v[16:31], v[104:107], v[96:99], v[16:31]
	s_waitcnt lgkmcnt(2)
	v_mfma_f32_32x32x16_bf16 v[16:31], v[108:111], v[6:9], v[16:31]
	s_waitcnt lgkmcnt(1)
	v_mfma_f32_32x32x16_bf16 v[16:31], v[112:115], v[80:83], v[16:31]
	s_waitcnt lgkmcnt(0)
	v_mfma_f32_32x32x16_bf16 v[16:31], v[116:119], v[10:13], v[16:31]
	v_fmac_f32_e32 v3, v139, v2
	v_mov_b32_e32 v139, v3
